# peel + relaxed vmcnt(8+S) in the peeled half-iteration behind epilogue stores, P1/P3 (S=16) and P7/P12 (S=8)
# baseline (speedup 1.0000x reference)
; #define PG8_STAGE(bufoff, gbase, voff) do { _Pragma("unroll") for (int _i = 0; _i < 2; ++_i) \
;         __builtin_amdgcn_global_load_lds((const unsigned*)((const char*)(gbase) + (voff)[_i]), (PG8_LAS unsigned*)(lds + (bufoff) + ldsw + _i * 8192), 16, 0, PG8_LOAD_AUX); } while (0)
; #define PG8_WAIT_V(n) asm volatile("s_waitcnt vmcnt(" #n ")" ::: "memory")
; #define PG8_BAR __builtin_amdgcn_s_barrier()
; template <class Epi, class Sched, bool ALIGN_EPI = false, bool SP2 = false>
; __device__ __forceinline__ void gemm_phase(PG8_LAS unsigned char* lds, const Gemm g, const Sched& S, const Epi& E) {
;     ...
;     for (int i = 0; i < 2; ++i) { int R, C; stage_rc(tid * 16 + i * 8192, R, C); const int Rb = Epi::WIDE ? (64 * (R >> 5) + perm32(R & 31)) : (Epi::PERM ? ((R & ~31) + perm32(R & 31)) : R);
;         voffA[i] = (unsigned)(R * lda + C) * 2u; voffB[i] = (unsigned)(Rb * K + C) * 2u; }
;     const size_t kstep = (size_t)(BK * 2);
;     const size_t hstepA = (size_t)HALF * lda * 2, hstepB = (size_t)(Epi::WIDE ? 32 : HALF) * K * 2;
;     const size_t tstepA = 2 * hstepA, tstepB = (size_t)BM * K * 2;
;     const size_t apn = (size_t)g.a_pn_off * 2;
;     const unsigned ldsw = (unsigned)wid * 1024u;
;     const int aoff = lds_byte(wr * 64 + fr, fq * 8), boff = lds_byte(wc * 32 + fr, fq * 8);
;     ...
;         PG8_WAIT_V(2); PG8_BAR;
;         PG8_STAGE(PG8_SB(1, 0), cB + kstep, voffB); PG8_STAGE(PG8_SA(1, 0), cA + kstep, voffA); PG8_STAGE(PG8_SB(1, 1), cB + hstepB + kstep, voffB);
;         PG8_WAIT_V(6); PG8_BAR;
.LBB0_209:
	s_mov_b64 s[10:11], 0x80
	s_and_b32 s14, s3, 3
	s_add_i32 m0, s42, 0x18000
	v_lshl_add_u64 v[6:7], v[6:7], 0, s[10:11]
	s_ashr_i32 s47, s86, 31
	s_lshl_b32 s15, s5, 13
	s_lshl_b32 s16, s14, 12
	s_waitcnt vmcnt(2)
	s_barrier
	global_load_lds_dwordx4 v[6:7], off
	v_lshl_add_u64 v[4:5], v[4:5], 0, s[10:11]
	s_add_i32 m0, s42, 0x1a000
	s_add_i32 s48, s42, 0x8000
	s_add_i32 s49, s42, 0xa000
	global_load_lds_dwordx4 v[4:5], off
	v_lshl_add_u64 v[0:1], v[0:1], 0, s[10:11]
	s_mov_b32 m0, s48
	s_add_u32 s12, s22, 0x10080
	global_load_lds_dwordx4 v[0:1], off
	v_lshl_add_u64 v[0:1], v[2:3], 0, s[10:11]
	s_mov_b32 m0, s49
	s_addc_u32 s13, s23, 0
	global_load_lds_dwordx4 v[0:1], off
	s_add_i32 m0, s42, 0x1c000
	v_lshl_add_u64 v[0:1], s[12:13], 0, v[130:131]
	global_load_lds_dwordx4 v[0:1], off
	v_lshl_add_u64 v[0:1], s[12:13], 0, v[134:135]
	s_add_i32 m0, s42, 0x1e000
	s_sext_i32_i16 s1, s2
	global_load_lds_dwordx4 v[0:1], off
	v_bfe_u32 v0, v154, 4, 2
	v_lshlrev_b32_e32 v2, 3, v0
	v_and_b32_e32 v1, 15, v154
	v_lshlrev_b32_e32 v3, 4, v0
	v_lshlrev_b32_e32 v0, 6, v154
	s_movk_i32 s2, 0x3c0
	v_lshl_or_b32 v147, s14, 6, v2
	v_lshlrev_b32_e32 v2, 8, v154
	v_and_or_b32 v4, v0, s2, v3
	v_cmp_gt_u32_e64 s[2:3], 8, v1
	v_lshl_or_b32 v1, v1, 6, v3
	v_and_b32_e32 v2, 0x38000, v2
	v_lshlrev_b32_e32 v3, 11, v10
	v_or3_b32 v2, v8, v2, v3
	v_lshlrev_b32_e32 v0, 2, v154
	v_add_u32_e32 v138, v2, v9
	v_lshlrev_b32_e32 v2, 4, v11
	v_and_b32_e32 v5, 32, v0
	v_and_b32_e32 v6, 7, v154
	s_waitcnt vmcnt(6)
	s_cmpk_lt_u32 s4, 0x100
	v_and_b32_e32 v2, 0x78000, v2
	v_cndmask_b32_e64 v0, 32, 0, s[2:3]
	v_bitop3_b32 v1, v1, s15, v5 bitop3:0xde
	v_bitop3_b32 v146, s16, v4, v5 bitop3:0xf6
	s_cselect_b64 s[12:13], -1, 0
	v_lshl_or_b32 v148, s5, 6, v6
	v_or3_b32 v2, v8, v2, v3
	s_add_i32 s51, 0, 0x10000
	s_add_i32 s52, 0, 0x14000
	s_mov_b32 s50, s86
	v_or_b32_e32 v149, 16, v148
	v_or_b32_e32 v150, 32, v148
	v_or_b32_e32 v151, 48, v148
	v_add_u32_e32 v152, 0x80, v148
	v_add_u32_e32 v155, 0x90, v148
	v_add_u32_e32 v156, 0xa0, v148
	v_add_u32_e32 v157, 0xb0, v148
	v_mov_b32_e32 v139, v137
	v_add_u32_e32 v140, v2, v9
	v_mov_b32_e32 v141, v137
	v_mov_b64_e32 v[142:143], 0x900
	v_mov_b64_e32 v[144:145], 0x8ff
	v_add_u32_e32 v158, s51, v146
	v_add_u32_e32 v159, s52, v146
	v_add_u32_e32 v160, 0, v1
	s_movk_i32 s53, 0x4800
	v_lshlrev_b32_e32 v136, 1, v0
	s_mov_b32 s54, 0x24000
	s_barrier
	s_mov_b32 s99, 0
	s_branch .LBB0_212

; #define PG8_STAGE(bufoff, gbase, voff) do { _Pragma("unroll") for (int _i = 0; _i < 2; ++_i) \
;         __builtin_amdgcn_global_load_lds((const unsigned*)((const char*)(gbase) + (voff)[_i]), (PG8_LAS unsigned*)(lds + (bufoff) + ldsw + _i * 8192), 16, 0, PG8_LOAD_AUX); } while (0)
; #define PG8_LDA(dst, b, h) do { _Pragma("unroll") for (int m = 0; m < 4; ++m) _Pragma("unroll") for (int k = 0; k < 2; ++k) dst[m][k] = *(const PG8_LAS bf16x8*)(lds + PG8_SA(b, h) + aoff + m * 2048 + k * 1024); } while (0)
; #define PG8_LDB(dst, b, h) do { _Pragma("unroll") for (int n = 0; n < 2; ++n) _Pragma("unroll") for (int k = 0; k < 2; ++k) dst[n][k] = *(const PG8_LAS bf16x8*)(lds + PG8_SB(b, h) + boff + n * 2048 + k * 1024); } while (0)
; #define PG8_WAIT_V(n) asm volatile("s_waitcnt vmcnt(" #n ")" ::: "memory")
; #define PG8_WAIT_L(n) asm volatile("s_waitcnt lgkmcnt(" #n ")" ::: "memory")
; #define PG8_BAR __builtin_amdgcn_s_barrier()
; #define PG8_SCHED __builtin_amdgcn_sched_barrier(0)
; template <class Epi, class Sched, bool ALIGN_EPI = false, bool SP2 = false>
; __device__ __forceinline__ void gemm_phase(PG8_LAS unsigned char* lds, const Gemm g, const Sched& S, const Epi& E) {
;     ...
;         const char* nA = has_next ? (const char*)g.A + (size_t)nxt.pm * tstepA + (size_t)nxt.pn * apn : cA; const char* nB = has_next ? (const char*)g.Bt + (size_t)nxt.pn * tstepB : cB;
;         for (int t = 0; t < nt; t += 2) {
;             const bool last = (t == nt - 2);
;             const char* a1 = cA + (size_t)(t + 1) * kstep;
;             const char* a2 = last ? nA : cA + (size_t)(t + 2) * kstep; const char* b2 = last ? nB : cB + (size_t)(t + 2) * kstep;
;             const char* a3 = a2 + kstep; const char* b3 = b2 + kstep;
;             if (last && has_next) S.a_ready(nxt);
;             if constexpr (SP2) {
;             PG8_LDB(B0, 0, 0); PG8_LDB(B1, 0, 1); PG8_SCHED; PG8_LDA(At, 0, 0); PG8_STAGE(PG8_SA(1, 1), a1 + hstepA, voffA);
;             PG8_WAIT_V(8); PG8_WAIT_L(0); PG8_BAR; PG8_MMA(0, 0, At, B0); PG8_MMA(0, 1, At, B1); PG8_BAR; PG8_SCHED;
;             PG8_LDA(At, 0, 1); PG8_STAGE(PG8_SB(0, 0), b2, voffB); PG8_STAGE(PG8_SB(0, 1), b2 + hstepB, voffB); PG8_STAGE(PG8_SA(0, 0), a2, voffA);
;             PG8_WAIT_V(8); PG8_WAIT_L(0); PG8_BAR; PG8_MMA(1, 0, At, B0); PG8_MMA(1, 1, At, B1); PG8_BAR; PG8_SCHED;
.LBB0_214:
	s_ashr_i32 s17, s16, 31
	s_lshl_b64 s[18:19], s[16:17], 19
	v_readlane_b32 s24, v239, 47
	v_readlane_b32 s25, v239, 48
	s_add_u32 s18, s24, s18
	s_addc_u32 s19, s25, s19
	s_and_b64 s[24:25], s[4:5], exec
	s_cselect_b32 s17, s19, s21
	s_cselect_b32 s24, s18, s20
	s_ashr_i32 s15, s14, 31
	s_lshl_b64 s[26:27], s[14:15], 19
	s_add_u32 s40, s64, s26
	s_addc_u32 s41, s65, s27
	s_and_b64 s[26:27], s[4:5], exec
	s_cselect_b32 s15, s41, s23
	s_cselect_b32 s25, s40, s22
	s_add_u32 s20, s20, 0x40080
	s_addc_u32 s21, s21, 0
	s_add_u32 s26, s22, 0x100
	s_addc_u32 s27, s23, 0
	s_mov_b32 s28, -2
	ds_read_b128 v[162:165], v158
	ds_read_b128 v[166:169], v158 offset:1024
	ds_read_b128 v[170:173], v158 offset:2048
	ds_read_b128 v[174:177], v158 offset:3072
	ds_read_b128 v[178:181], v159
	ds_read_b128 v[182:185], v159 offset:1024
	ds_read_b128 v[186:189], v159 offset:2048
	ds_read_b128 v[190:193], v159 offset:3072
	s_add_u32 s22, s20, 0xfffc0080
	s_addc_u32 s23, s21, -1
	s_cmp_eq_u32 s28, 12
	s_cselect_b32 s35, s17, s23
	s_cselect_b32 s34, s24, s22
	s_cselect_b32 s23, s15, s27
	s_cselect_b32 s22, s25, s26
	v_lshl_add_u64 v[226:227], s[20:21], 0, v[138:139]
	s_add_i32 m0, s42, 0xc000
	ds_read_b128 v[194:197], v160
	ds_read_b128 v[198:201], v160 offset:1024
	ds_read_b128 v[202:205], v160 offset:2048
	ds_read_b128 v[206:209], v160 offset:3072
	ds_read_b128 v[210:213], v160 offset:4096
	ds_read_b128 v[214:217], v160 offset:5120
	ds_read_b128 v[218:221], v160 offset:6144
	ds_read_b128 v[222:225], v160 offset:7168
	global_load_lds_dwordx4 v[226:227], off
	v_lshl_add_u64 v[226:227], s[20:21], 0, v[140:141]
	s_add_i32 m0, s42, 0xe000
	s_nop 0
	global_load_lds_dwordx4 v[226:227], off
	s_cmp_lg_u32 s99, 0
	s_cbranch_scc1 .Lrw_P1_0r
	s_waitcnt vmcnt(8)
	s_branch .Lrw_P1_0d
.Lrw_P1_0r:
	s_waitcnt vmcnt(24)
.Lrw_P1_0d:
	s_waitcnt lgkmcnt(0)
	s_barrier
	s_setprio 1
	s_waitcnt lgkmcnt(0)
	v_mfma_f32_16x16x32_bf16 v[124:127], v[162:165], v[194:197], 0
	v_mfma_f32_16x16x32_bf16 v[120:123], v[170:173], v[194:197], 0
	v_mfma_f32_16x16x32_bf16 v[108:111], v[162:165], v[202:205], 0
	v_mfma_f32_16x16x32_bf16 v[104:107], v[170:173], v[202:205], 0
	v_mfma_f32_16x16x32_bf16 v[92:95], v[162:165], v[210:213], 0
	v_mfma_f32_16x16x32_bf16 v[88:91], v[170:173], v[210:213], 0
	v_mfma_f32_16x16x32_bf16 v[76:79], v[162:165], v[218:221], 0
	v_mfma_f32_16x16x32_bf16 v[72:75], v[170:173], v[218:221], 0
	v_mfma_f32_16x16x32_bf16 v[124:127], v[166:169], v[198:201], v[124:127]
	v_mfma_f32_16x16x32_bf16 v[120:123], v[174:177], v[198:201], v[120:123]
	v_mfma_f32_16x16x32_bf16 v[108:111], v[166:169], v[206:209], v[108:111]
	v_mfma_f32_16x16x32_bf16 v[104:107], v[174:177], v[206:209], v[104:107]
	v_mfma_f32_16x16x32_bf16 v[92:95], v[166:169], v[214:217], v[92:95]
	v_mfma_f32_16x16x32_bf16 v[88:91], v[174:177], v[214:217], v[88:91]
	v_mfma_f32_16x16x32_bf16 v[76:79], v[166:169], v[222:225], v[76:79]
	v_mfma_f32_16x16x32_bf16 v[72:75], v[174:177], v[222:225], v[72:75]
	s_setprio 0
	s_setprio 1
	v_mfma_f32_16x16x32_bf16 v[116:119], v[178:181], v[194:197], 0
	v_mfma_f32_16x16x32_bf16 v[112:115], v[186:189], v[194:197], 0
	v_mfma_f32_16x16x32_bf16 v[100:103], v[178:181], v[202:205], 0
	v_mfma_f32_16x16x32_bf16 v[96:99], v[186:189], v[202:205], 0
	v_mfma_f32_16x16x32_bf16 v[84:87], v[178:181], v[210:213], 0
	v_mfma_f32_16x16x32_bf16 v[80:83], v[186:189], v[210:213], 0
	v_mfma_f32_16x16x32_bf16 v[68:71], v[178:181], v[218:221], 0
	v_mfma_f32_16x16x32_bf16 v[64:67], v[186:189], v[218:221], 0
	v_mfma_f32_16x16x32_bf16 v[116:119], v[182:185], v[198:201], v[116:119]
	v_mfma_f32_16x16x32_bf16 v[112:115], v[190:193], v[198:201], v[112:115]
	v_mfma_f32_16x16x32_bf16 v[100:103], v[182:185], v[206:209], v[100:103]
	v_mfma_f32_16x16x32_bf16 v[96:99], v[190:193], v[206:209], v[96:99]
	v_mfma_f32_16x16x32_bf16 v[84:87], v[182:185], v[214:217], v[84:87]
	v_mfma_f32_16x16x32_bf16 v[80:83], v[190:193], v[214:217], v[80:83]
	v_mfma_f32_16x16x32_bf16 v[68:71], v[182:185], v[222:225], v[68:71]
	v_mfma_f32_16x16x32_bf16 v[64:67], v[190:193], v[222:225], v[64:67]
	s_setprio 0
	s_barrier
	s_add_i32 s29, s51, s33
	v_lshl_add_u64 v[226:227], s[22:23], 0, v[130:131]
	s_mov_b32 m0, s29
	ds_read_b128 v[194:197], v160 offset:16384
	ds_read_b128 v[198:201], v160 offset:17408
	ds_read_b128 v[202:205], v160 offset:18432
	ds_read_b128 v[206:209], v160 offset:19456
	ds_read_b128 v[210:213], v160 offset:20480
	ds_read_b128 v[214:217], v160 offset:21504
	ds_read_b128 v[218:221], v160 offset:22528
	ds_read_b128 v[222:225], v160 offset:23552
	global_load_lds_dwordx4 v[226:227], off
	s_add_i32 m0, s29, 0x2000
	s_add_u32 s30, s22, 0x10000
	v_lshl_add_u64 v[228:229], s[22:23], 0, v[134:135]
	s_addc_u32 s31, s23, 0
	s_add_i32 s29, s52, s33
	global_load_lds_dwordx4 v[228:229], off
	v_lshl_add_u64 v[230:231], s[30:31], 0, v[130:131]
	s_mov_b32 m0, s29
	v_lshl_add_u64 v[232:233], s[34:35], 0, v[132:133]
	global_load_lds_dwordx4 v[230:231], off
	v_lshl_add_u64 v[230:231], s[30:31], 0, v[134:135]
	s_add_i32 m0, s29, 0x2000
	s_nop 0
	global_load_lds_dwordx4 v[230:231], off
	v_lshl_add_u64 v[230:231], s[34:35], 0, v[128:129]
	s_mov_b32 m0, s42
	s_nop 0
	global_load_lds_dwordx4 v[230:231], off
	s_mov_b32 m0, s43
	s_nop 0
	global_load_lds_dwordx4 v[232:233], off
	s_cmp_lg_u32 s99, 0
	s_cbranch_scc1 .Lrw_P1_1r
	s_waitcnt vmcnt(8)
	s_branch .Lrw_P1_1d

; #define PG8_MMA(ai, bj, At, Bt) do { __builtin_amdgcn_s_setprio(1); _Pragma("unroll") for (int m = 0; m < 4; ++m) _Pragma("unroll") for (int n = 0; n < 2; ++n) _Pragma("unroll") for (int k = 0; k < 2; ++k) \
;         acc[ai][bj][m][n] = __builtin_amdgcn_mfma_f32_16x16x32_bf16(Bt[n][k], At[m][k], acc[ai][bj][m][n], 0, 0, 0); __builtin_amdgcn_s_setprio(0); } while (0)
; #define PG8_WAIT_V(n) asm volatile("s_waitcnt vmcnt(" #n ")" ::: "memory")
; #define PG8_WAIT_L(n) asm volatile("s_waitcnt lgkmcnt(" #n ")" ::: "memory")
; #define PG8_BAR __builtin_amdgcn_s_barrier()
; #define PG8_SCHED __builtin_amdgcn_sched_barrier(0)
; template <class Epi, class Sched, bool ALIGN_EPI = false, bool SP2 = false>
; __device__ __forceinline__ void gemm_phase(PG8_LAS unsigned char* lds, const Gemm g, const Sched& S, const Epi& E) {
;     ...
;             PG8_WAIT_V(8); PG8_WAIT_L(0); PG8_BAR; PG8_MMA(1, 0, At, B0); PG8_MMA(1, 1, At, B1); PG8_BAR; PG8_SCHED;
.Lrw_P1_1d:
	s_waitcnt lgkmcnt(0)
	s_barrier
	s_setprio 1
	s_waitcnt lgkmcnt(0)
	v_mfma_f32_16x16x32_bf16 v[60:63], v[162:165], v[194:197], 0
	v_mfma_f32_16x16x32_bf16 v[56:59], v[170:173], v[194:197], 0
	v_mfma_f32_16x16x32_bf16 v[44:47], v[162:165], v[202:205], 0
	v_mfma_f32_16x16x32_bf16 v[40:43], v[170:173], v[202:205], 0
	v_mfma_f32_16x16x32_bf16 v[28:31], v[162:165], v[210:213], 0
	v_mfma_f32_16x16x32_bf16 v[24:27], v[170:173], v[210:213], 0
	v_mfma_f32_16x16x32_bf16 v[12:15], v[162:165], v[218:221], 0
	v_mfma_f32_16x16x32_bf16 v[8:11], v[170:173], v[218:221], 0
	v_mfma_f32_16x16x32_bf16 v[60:63], v[166:169], v[198:201], v[60:63]
	v_mfma_f32_16x16x32_bf16 v[56:59], v[174:177], v[198:201], v[56:59]
	v_mfma_f32_16x16x32_bf16 v[44:47], v[166:169], v[206:209], v[44:47]
	v_mfma_f32_16x16x32_bf16 v[40:43], v[174:177], v[206:209], v[40:43]
	v_mfma_f32_16x16x32_bf16 v[28:31], v[166:169], v[214:217], v[28:31]
	v_mfma_f32_16x16x32_bf16 v[24:27], v[174:177], v[214:217], v[24:27]
	v_mfma_f32_16x16x32_bf16 v[12:15], v[166:169], v[222:225], v[12:15]
	v_mfma_f32_16x16x32_bf16 v[8:11], v[174:177], v[222:225], v[8:11]
	s_setprio 0
	s_setprio 1
	v_mfma_f32_16x16x32_bf16 v[52:55], v[178:181], v[194:197], 0
	v_mfma_f32_16x16x32_bf16 v[48:51], v[186:189], v[194:197], 0
	v_mfma_f32_16x16x32_bf16 v[36:39], v[178:181], v[202:205], 0
	v_mfma_f32_16x16x32_bf16 v[32:35], v[186:189], v[202:205], 0
	v_mfma_f32_16x16x32_bf16 v[20:23], v[178:181], v[210:213], 0
	v_mfma_f32_16x16x32_bf16 v[16:19], v[186:189], v[210:213], 0
	v_mfma_f32_16x16x32_bf16 v[4:7], v[178:181], v[218:221], 0
	v_mfma_f32_16x16x32_bf16 v[0:3], v[186:189], v[218:221], 0
	v_mfma_f32_16x16x32_bf16 v[52:55], v[182:185], v[198:201], v[52:55]
	v_mfma_f32_16x16x32_bf16 v[48:51], v[190:193], v[198:201], v[48:51]
	v_mfma_f32_16x16x32_bf16 v[36:39], v[182:185], v[206:209], v[36:39]
	v_mfma_f32_16x16x32_bf16 v[32:35], v[190:193], v[206:209], v[32:35]
	v_mfma_f32_16x16x32_bf16 v[20:23], v[182:185], v[214:217], v[20:23]
	v_mfma_f32_16x16x32_bf16 v[16:19], v[190:193], v[214:217], v[16:19]
	v_mfma_f32_16x16x32_bf16 v[4:7], v[182:185], v[222:225], v[4:7]
	v_mfma_f32_16x16x32_bf16 v[0:3], v[190:193], v[222:225], v[0:3]
	s_setprio 0
	s_barrier
	s_branch .Lkmid_P1

; #define PG8_STAGE(bufoff, gbase, voff) do { _Pragma("unroll") for (int _i = 0; _i < 2; ++_i) \
;         __builtin_amdgcn_global_load_lds((const unsigned*)((const char*)(gbase) + (voff)[_i]), (PG8_LAS unsigned*)(lds + (bufoff) + ldsw + _i * 8192), 16, 0, PG8_LOAD_AUX); } while (0)
; #define PG8_LDA(dst, b, h) do { _Pragma("unroll") for (int m = 0; m < 4; ++m) _Pragma("unroll") for (int k = 0; k < 2; ++k) dst[m][k] = *(const PG8_LAS bf16x8*)(lds + PG8_SA(b, h) + aoff + m * 2048 + k * 1024); } while (0)
; #define PG8_LDB(dst, b, h) do { _Pragma("unroll") for (int n = 0; n < 2; ++n) _Pragma("unroll") for (int k = 0; k < 2; ++k) dst[n][k] = *(const PG8_LAS bf16x8*)(lds + PG8_SB(b, h) + boff + n * 2048 + k * 1024); } while (0)
; #define PG8_MMA(ai, bj, At, Bt) do { __builtin_amdgcn_s_setprio(1); _Pragma("unroll") for (int m = 0; m < 4; ++m) _Pragma("unroll") for (int n = 0; n < 2; ++n) _Pragma("unroll") for (int k = 0; k < 2; ++k) \
;         acc[ai][bj][m][n] = __builtin_amdgcn_mfma_f32_16x16x32_bf16(Bt[n][k], At[m][k], acc[ai][bj][m][n], 0, 0, 0); __builtin_amdgcn_s_setprio(0); } while (0)
; #define PG8_WAIT_V(n) asm volatile("s_waitcnt vmcnt(" #n ")" ::: "memory")
; #define PG8_WAIT_L(n) asm volatile("s_waitcnt lgkmcnt(" #n ")" ::: "memory")
; #define PG8_BAR __builtin_amdgcn_s_barrier()
; #define PG8_SCHED __builtin_amdgcn_sched_barrier(0)
; template <class Epi, class Sched, bool ALIGN_EPI = false, bool SP2 = false>
; __device__ __forceinline__ void gemm_phase(PG8_LAS unsigned char* lds, const Gemm g, const Sched& S, const Epi& E) {
;     ...
;             PG8_LDB(B0, 1, 0); PG8_LDB(B1, 1, 1); PG8_SCHED; PG8_LDA(At, 1, 0); PG8_STAGE(PG8_SA(0, 1), a2 + hstepA, voffA);
;             PG8_WAIT_V(8); PG8_WAIT_L(0); PG8_BAR; PG8_MMA(0, 0, At, B0); PG8_MMA(0, 1, At, B1); PG8_BAR; PG8_SCHED;
.Lkmid_P1:
	s_add_i32 s29, 0, 0x18000
	v_add_u32_e32 v161, s29, v146
	s_add_i32 s38, 0, 0x1c000
	ds_read_b128 v[162:165], v161
	ds_read_b128 v[166:169], v161 offset:1024
	ds_read_b128 v[170:173], v161 offset:2048
	ds_read_b128 v[174:177], v161 offset:3072
	v_add_u32_e32 v161, s38, v146
	ds_read_b128 v[178:181], v161
	ds_read_b128 v[182:185], v161 offset:1024
	ds_read_b128 v[186:189], v161 offset:2048
	ds_read_b128 v[190:193], v161 offset:3072
	s_add_u32 s30, s34, 0x40000
	s_addc_u32 s31, s35, 0
	s_mov_b32 m0, s44
	v_lshl_add_u64 v[234:235], s[30:31], 0, v[128:129]
	ds_read_b128 v[194:197], v160 offset:32768
	ds_read_b128 v[198:201], v160 offset:33792
	ds_read_b128 v[202:205], v160 offset:34816
	ds_read_b128 v[206:209], v160 offset:35840
	ds_read_b128 v[210:213], v160 offset:36864
	ds_read_b128 v[214:217], v160 offset:37888
	ds_read_b128 v[218:221], v160 offset:38912
	ds_read_b128 v[222:225], v160 offset:39936
	global_load_lds_dwordx4 v[234:235], off
	v_lshl_add_u64 v[234:235], s[30:31], 0, v[132:133]
	s_mov_b32 m0, s45
	s_nop 0
	global_load_lds_dwordx4 v[234:235], off
	s_waitcnt vmcnt(8)
	s_waitcnt lgkmcnt(0)
	s_barrier
	s_setprio 1
	s_waitcnt lgkmcnt(0)
	v_mfma_f32_16x16x32_bf16 v[124:127], v[162:165], v[194:197], v[124:127]
	v_mfma_f32_16x16x32_bf16 v[120:123], v[170:173], v[194:197], v[120:123]
	v_mfma_f32_16x16x32_bf16 v[108:111], v[162:165], v[202:205], v[108:111]
	v_mfma_f32_16x16x32_bf16 v[104:107], v[170:173], v[202:205], v[104:107]
	v_mfma_f32_16x16x32_bf16 v[92:95], v[162:165], v[210:213], v[92:95]
	v_mfma_f32_16x16x32_bf16 v[88:91], v[170:173], v[210:213], v[88:91]
	v_mfma_f32_16x16x32_bf16 v[76:79], v[162:165], v[218:221], v[76:79]
	v_mfma_f32_16x16x32_bf16 v[72:75], v[170:173], v[218:221], v[72:75]
	v_mfma_f32_16x16x32_bf16 v[124:127], v[166:169], v[198:201], v[124:127]
	v_mfma_f32_16x16x32_bf16 v[120:123], v[174:177], v[198:201], v[120:123]
	v_mfma_f32_16x16x32_bf16 v[108:111], v[166:169], v[206:209], v[108:111]
	v_mfma_f32_16x16x32_bf16 v[104:107], v[174:177], v[206:209], v[104:107]
	v_mfma_f32_16x16x32_bf16 v[92:95], v[166:169], v[214:217], v[92:95]
	v_mfma_f32_16x16x32_bf16 v[88:91], v[174:177], v[214:217], v[88:91]
	v_mfma_f32_16x16x32_bf16 v[76:79], v[166:169], v[222:225], v[76:79]
	v_mfma_f32_16x16x32_bf16 v[72:75], v[174:177], v[222:225], v[72:75]
	s_setprio 0
	s_setprio 1
	v_mfma_f32_16x16x32_bf16 v[116:119], v[178:181], v[194:197], v[116:119]
	v_mfma_f32_16x16x32_bf16 v[112:115], v[186:189], v[194:197], v[112:115]
	v_mfma_f32_16x16x32_bf16 v[100:103], v[178:181], v[202:205], v[100:103]
	v_mfma_f32_16x16x32_bf16 v[96:99], v[186:189], v[202:205], v[96:99]
	v_mfma_f32_16x16x32_bf16 v[84:87], v[178:181], v[210:213], v[84:87]
	v_mfma_f32_16x16x32_bf16 v[80:83], v[186:189], v[210:213], v[80:83]
	v_mfma_f32_16x16x32_bf16 v[68:71], v[178:181], v[218:221], v[68:71]
	v_mfma_f32_16x16x32_bf16 v[64:67], v[186:189], v[218:221], v[64:67]
	v_mfma_f32_16x16x32_bf16 v[116:119], v[182:185], v[198:201], v[116:119]
	v_mfma_f32_16x16x32_bf16 v[112:115], v[190:193], v[198:201], v[112:115]
	v_mfma_f32_16x16x32_bf16 v[100:103], v[182:185], v[206:209], v[100:103]
	v_mfma_f32_16x16x32_bf16 v[96:99], v[190:193], v[206:209], v[96:99]
	v_mfma_f32_16x16x32_bf16 v[84:87], v[182:185], v[214:217], v[84:87]
	v_mfma_f32_16x16x32_bf16 v[80:83], v[190:193], v[214:217], v[80:83]
	v_mfma_f32_16x16x32_bf16 v[68:71], v[182:185], v[222:225], v[68:71]
	v_mfma_f32_16x16x32_bf16 v[64:67], v[190:193], v[222:225], v[64:67]
	s_setprio 0
	s_barrier
; #define PG8_STAGE(bufoff, gbase, voff) do { _Pragma("unroll") for (int _i = 0; _i < 2; ++_i) \
;         __builtin_amdgcn_global_load_lds((const unsigned*)((const char*)(gbase) + (voff)[_i]), (PG8_LAS unsigned*)(lds + (bufoff) + ldsw + _i * 8192), 16, 0, PG8_LOAD_AUX); } while (0)
; #define PG8_LDA(dst, b, h) do { _Pragma("unroll") for (int m = 0; m < 4; ++m) _Pragma("unroll") for (int k = 0; k < 2; ++k) dst[m][k] = *(const PG8_LAS bf16x8*)(lds + PG8_SA(b, h) + aoff + m * 2048 + k * 1024); } while (0)
; #define PG8_MMA(ai, bj, At, Bt) do { __builtin_amdgcn_s_setprio(1); _Pragma("unroll") for (int m = 0; m < 4; ++m) _Pragma("unroll") for (int n = 0; n < 2; ++n) _Pragma("unroll") for (int k = 0; k < 2; ++k) \
;         acc[ai][bj][m][n] = __builtin_amdgcn_mfma_f32_16x16x32_bf16(Bt[n][k], At[m][k], acc[ai][bj][m][n], 0, 0, 0); __builtin_amdgcn_s_setprio(0); } while (0)
; #define PG8_WAIT_V(n) asm volatile("s_waitcnt vmcnt(" #n ")" ::: "memory")
; #define PG8_WAIT_L(n) asm volatile("s_waitcnt lgkmcnt(" #n ")" ::: "memory")
; #define PG8_BAR __builtin_amdgcn_s_barrier()
; #define PG8_SCHED __builtin_amdgcn_sched_barrier(0)
; template <class Epi, class Sched, bool ALIGN_EPI = false, bool SP2 = false>
; __device__ __forceinline__ void gemm_phase(PG8_LAS unsigned char* lds, const Gemm g, const Sched& S, const Epi& E) {
;     ...
;             PG8_LDA(At, 1, 1); PG8_STAGE(PG8_SB(1, 0), b3, voffB); PG8_STAGE(PG8_SB(1, 1), b3 + hstepB, voffB); PG8_STAGE(PG8_SA(1, 0), a3, voffA);
;             PG8_WAIT_V(8); PG8_WAIT_L(0); PG8_BAR; PG8_MMA(1, 0, At, B0); PG8_MMA(1, 1, At, B1); PG8_BAR; PG8_SCHED;
;     ...
;         if constexpr (ALIGN_EPI) { if (wr == 0) PG8_BAR; }
	s_add_i32 s29, s29, s33
	v_lshl_add_u64 v[226:227], v[226:227], 0, s[10:11]
	s_mov_b32 m0, s29
	ds_read_b128 v[194:197], v160 offset:49152
	ds_read_b128 v[198:201], v160 offset:50176
	ds_read_b128 v[202:205], v160 offset:51200
	ds_read_b128 v[206:209], v160 offset:52224
	ds_read_b128 v[210:213], v160 offset:53248
	ds_read_b128 v[214:217], v160 offset:54272
	ds_read_b128 v[218:221], v160 offset:55296
	ds_read_b128 v[222:225], v160 offset:56320
	global_load_lds_dwordx4 v[226:227], off
	s_add_i32 m0, s29, 0x2000
	s_add_u32 s22, s22, 0x10080
	v_lshl_add_u64 v[226:227], v[228:229], 0, s[10:11]
	s_addc_u32 s23, s23, 0
	s_add_i32 s29, s38, s33
	global_load_lds_dwordx4 v[226:227], off
	v_lshl_add_u64 v[226:227], s[22:23], 0, v[130:131]
	s_mov_b32 m0, s29
	s_nop 0
	global_load_lds_dwordx4 v[226:227], off
	v_lshl_add_u64 v[226:227], s[22:23], 0, v[134:135]
	s_add_i32 m0, s29, 0x2000
	s_nop 0
	global_load_lds_dwordx4 v[226:227], off
	v_lshl_add_u64 v[226:227], v[230:231], 0, s[10:11]
	s_mov_b32 m0, s48
	s_nop 0
	global_load_lds_dwordx4 v[226:227], off
	v_lshl_add_u64 v[226:227], v[232:233], 0, s[10:11]
	s_mov_b32 m0, s49
	s_nop 0
	global_load_lds_dwordx4 v[226:227], off
	s_waitcnt vmcnt(8)
	s_waitcnt lgkmcnt(0)
	s_barrier
	s_setprio 1
	s_waitcnt lgkmcnt(0)
	v_mfma_f32_16x16x32_bf16 v[60:63], v[162:165], v[194:197], v[60:63]
	v_mfma_f32_16x16x32_bf16 v[56:59], v[170:173], v[194:197], v[56:59]
	v_mfma_f32_16x16x32_bf16 v[44:47], v[162:165], v[202:205], v[44:47]
	v_mfma_f32_16x16x32_bf16 v[40:43], v[170:173], v[202:205], v[40:43]
	v_mfma_f32_16x16x32_bf16 v[28:31], v[162:165], v[210:213], v[28:31]
	v_mfma_f32_16x16x32_bf16 v[24:27], v[170:173], v[210:213], v[24:27]
	v_mfma_f32_16x16x32_bf16 v[12:15], v[162:165], v[218:221], v[12:15]
	v_mfma_f32_16x16x32_bf16 v[8:11], v[170:173], v[218:221], v[8:11]
	v_mfma_f32_16x16x32_bf16 v[60:63], v[166:169], v[198:201], v[60:63]
	v_mfma_f32_16x16x32_bf16 v[56:59], v[174:177], v[198:201], v[56:59]
	v_mfma_f32_16x16x32_bf16 v[44:47], v[166:169], v[206:209], v[44:47]
	v_mfma_f32_16x16x32_bf16 v[40:43], v[174:177], v[206:209], v[40:43]
	v_mfma_f32_16x16x32_bf16 v[28:31], v[166:169], v[214:217], v[28:31]
	v_mfma_f32_16x16x32_bf16 v[24:27], v[174:177], v[214:217], v[24:27]
	v_mfma_f32_16x16x32_bf16 v[12:15], v[166:169], v[222:225], v[12:15]
	v_mfma_f32_16x16x32_bf16 v[8:11], v[174:177], v[222:225], v[8:11]
	s_setprio 0
	s_setprio 1
	v_mfma_f32_16x16x32_bf16 v[52:55], v[178:181], v[194:197], v[52:55]
	v_mfma_f32_16x16x32_bf16 v[48:51], v[186:189], v[194:197], v[48:51]
	v_mfma_f32_16x16x32_bf16 v[36:39], v[178:181], v[202:205], v[36:39]
	v_mfma_f32_16x16x32_bf16 v[32:35], v[186:189], v[202:205], v[32:35]
	v_mfma_f32_16x16x32_bf16 v[20:23], v[178:181], v[210:213], v[20:23]
	v_mfma_f32_16x16x32_bf16 v[16:19], v[186:189], v[210:213], v[16:19]
	v_mfma_f32_16x16x32_bf16 v[4:7], v[178:181], v[218:221], v[4:7]
	v_mfma_f32_16x16x32_bf16 v[0:3], v[186:189], v[218:221], v[0:3]
	v_mfma_f32_16x16x32_bf16 v[52:55], v[182:185], v[198:201], v[52:55]
	v_mfma_f32_16x16x32_bf16 v[48:51], v[190:193], v[198:201], v[48:51]
	v_mfma_f32_16x16x32_bf16 v[36:39], v[182:185], v[206:209], v[36:39]
	v_mfma_f32_16x16x32_bf16 v[32:35], v[190:193], v[206:209], v[32:35]
	v_mfma_f32_16x16x32_bf16 v[20:23], v[182:185], v[214:217], v[20:23]
	v_mfma_f32_16x16x32_bf16 v[16:19], v[190:193], v[214:217], v[16:19]
	v_mfma_f32_16x16x32_bf16 v[4:7], v[182:185], v[222:225], v[4:7]
	v_mfma_f32_16x16x32_bf16 v[0:3], v[190:193], v[222:225], v[0:3]
	s_setprio 0
	s_barrier
	s_add_i32 s28, s28, 2
	s_add_u32 s20, s20, 0x100
	s_addc_u32 s21, s21, 0
	s_add_u32 s26, s26, 0x100
	s_addc_u32 s27, s27, 0
	s_cmp_gt_u32 s28, 13
	s_cbranch_scc0 .LBB0_215
	s_mov_b32 s99, 1
	s_and_b64 vcc, exec, s[12:13]
	s_cbranch_vccz .LBB0_218
	s_barrier

; #define PG8_STAGE(bufoff, gbase, voff) do { _Pragma("unroll") for (int _i = 0; _i < 2; ++_i) \
;         __builtin_amdgcn_global_load_lds((const unsigned*)((const char*)(gbase) + (voff)[_i]), (PG8_LAS unsigned*)(lds + (bufoff) + ldsw + _i * 8192), 16, 0, PG8_LOAD_AUX); } while (0)
; #define PG8_WAIT_V(n) asm volatile("s_waitcnt vmcnt(" #n ")" ::: "memory")
; #define PG8_BAR __builtin_amdgcn_s_barrier()
; template <class Epi, class Sched, bool ALIGN_EPI = false, bool SP2 = false>
; __device__ __forceinline__ void gemm_phase(PG8_LAS unsigned char* lds, const Gemm g, const Sched& S, const Epi& E) {
;     ...
;     for (int i = 0; i < 2; ++i) { int R, C; stage_rc(tid * 16 + i * 8192, R, C); const int Rb = Epi::WIDE ? (64 * (R >> 5) + perm32(R & 31)) : (Epi::PERM ? ((R & ~31) + perm32(R & 31)) : R);
;         voffA[i] = (unsigned)(R * lda + C) * 2u; voffB[i] = (unsigned)(Rb * K + C) * 2u; }
;     const size_t kstep = (size_t)(BK * 2);
;     const size_t hstepA = (size_t)HALF * lda * 2, hstepB = (size_t)(Epi::WIDE ? 32 : HALF) * K * 2;
;     const size_t tstepA = 2 * hstepA, tstepB = (size_t)BM * K * 2;
;     const size_t apn = (size_t)g.a_pn_off * 2;
;     const unsigned ldsw = (unsigned)wid * 1024u;
;     const int aoff = lds_byte(wr * 64 + fr, fq * 8), boff = lds_byte(wc * 32 + fr, fq * 8);
;     ...
;         PG8_WAIT_V(2); PG8_BAR;
;         PG8_STAGE(PG8_SB(1, 0), cB + kstep, voffB); PG8_STAGE(PG8_SA(1, 0), cA + kstep, voffA); PG8_STAGE(PG8_SB(1, 1), cB + hstepB + kstep, voffB);
;         PG8_WAIT_V(6); PG8_BAR;
.LBB0_363:
	s_mov_b64 s[10:11], 0x80
	s_and_b32 s14, s5, 3
	s_add_i32 m0, s44, 0x18000
	v_lshl_add_u64 v[6:7], v[6:7], 0, s[10:11]
	s_lshl_b32 s15, s4, 6
	s_lshl_b32 s1, s4, 13
	s_lshl_b32 s12, s14, 12
	s_waitcnt vmcnt(2)
	s_barrier
	global_load_lds_dwordx4 v[6:7], off
	v_lshl_add_u64 v[4:5], v[4:5], 0, s[10:11]
	s_add_i32 m0, s44, 0x1a000
	s_add_i32 s49, s44, 0x8000
	s_add_i32 s50, s44, 0xa000
	global_load_lds_dwordx4 v[4:5], off
	v_lshl_add_u64 v[0:1], v[0:1], 0, s[10:11]
	s_mov_b32 m0, s49
	s_add_u32 s4, s22, 0x10080
	global_load_lds_dwordx4 v[0:1], off
	v_lshl_add_u64 v[0:1], v[2:3], 0, s[10:11]
	s_mov_b32 m0, s50
	s_addc_u32 s5, s23, 0
	global_load_lds_dwordx4 v[0:1], off
	s_add_i32 m0, s44, 0x1c000
	v_lshl_add_u64 v[0:1], s[4:5], 0, v[132:133]
	global_load_lds_dwordx4 v[0:1], off
	v_lshl_add_u64 v[0:1], s[4:5], 0, v[128:129]
	s_add_i32 m0, s44, 0x1e000
	v_lshlrev_b32_e32 v4, 2, v154
	global_load_lds_dwordx4 v[0:1], off
	v_bfe_u32 v1, v154, 4, 2
	v_and_b32_e32 v0, 15, v154
	v_lshlrev_b32_e32 v2, 3, v1
	v_lshlrev_b32_e32 v1, 4, v1
	v_lshl_or_b32 v3, v0, 6, v1
	v_and_b32_e32 v4, 32, v4
	v_bitop3_b32 v3, v3, s1, v4 bitop3:0xde
	v_lshlrev_b32_e32 v5, 6, v154
	s_movk_i32 s1, 0x3c0
	v_and_or_b32 v1, v5, s1, v1
	s_cmpk_lt_u32 s3, 0x100
	v_bitop3_b32 v146, s12, v1, v4 bitop3:0xf6
	s_cselect_b64 s[12:13], -1, 0
	v_lshl_or_b32 v147, s14, 6, v2
	v_and_b32_e32 v1, 7, v154
	s_add_i32 s4, s15, 0x80
	s_add_i32 s5, s15, 0x90
	s_add_i32 s14, s15, 0xa0
	s_add_i32 s16, s15, 0xb0
	v_or_b32_e32 v148, s15, v1
	v_or_b32_e32 v152, s4, v1
	v_or_b32_e32 v156, s5, v1
	v_or_b32_e32 v157, s14, v1
	v_or_b32_e32 v158, s16, v1
	v_lshlrev_b32_e32 v1, 8, v154
	v_and_b32_e32 v1, 0x38000, v1
	v_lshlrev_b32_e32 v2, 11, v11
	v_or3_b32 v1, v9, v1, v2
	v_add_u32_e32 v138, v1, v10
	v_lshlrev_b32_e32 v1, 4, v8
	s_sext_i32_i16 s1, s2
	s_waitcnt vmcnt(6)
	v_cmp_gt_u32_e64 s[2:3], 8, v0
	v_and_b32_e32 v1, 0x78000, v1
	v_or3_b32 v1, v9, v1, v2
	v_cndmask_b32_e64 v0, 32, 0, s[2:3]
	s_add_i32 s53, 0, 0x10000
	s_add_i32 s54, 0, 0x14000
	s_ashr_i32 s51, s86, 31
	s_mov_b32 s52, s86
	v_or_b32_e32 v149, 16, v148
	v_or_b32_e32 v150, 32, v148
	v_or_b32_e32 v151, 48, v148
	v_mov_b32_e32 v139, v137
	v_add_u32_e32 v140, v1, v10
	v_mov_b32_e32 v141, v137
	v_mov_b64_e32 v[142:143], 0x900
	v_mov_b64_e32 v[144:145], 0x8ff
	v_add_u32_e32 v159, s53, v146
	v_add_u32_e32 v160, s54, v146
	v_add_u32_e32 v161, 0, v3
	s_movk_i32 s55, 0x4800
	v_lshlrev_b32_e32 v136, 1, v0
	s_mov_b32 s56, 0x24000
	s_barrier
	s_mov_b32 s99, 0
	s_branch .LBB0_366

; #define PG8_STAGE(bufoff, gbase, voff) do { _Pragma("unroll") for (int _i = 0; _i < 2; ++_i) \
;         __builtin_amdgcn_global_load_lds((const unsigned*)((const char*)(gbase) + (voff)[_i]), (PG8_LAS unsigned*)(lds + (bufoff) + ldsw + _i * 8192), 16, 0, PG8_LOAD_AUX); } while (0)
; #define PG8_LDA(dst, b, h) do { _Pragma("unroll") for (int m = 0; m < 4; ++m) _Pragma("unroll") for (int k = 0; k < 2; ++k) dst[m][k] = *(const PG8_LAS bf16x8*)(lds + PG8_SA(b, h) + aoff + m * 2048 + k * 1024); } while (0)
; #define PG8_LDB(dst, b, h) do { _Pragma("unroll") for (int n = 0; n < 2; ++n) _Pragma("unroll") for (int k = 0; k < 2; ++k) dst[n][k] = *(const PG8_LAS bf16x8*)(lds + PG8_SB(b, h) + boff + n * 2048 + k * 1024); } while (0)
; #define PG8_MMA(ai, bj, At, Bt) do { __builtin_amdgcn_s_setprio(1); _Pragma("unroll") for (int m = 0; m < 4; ++m) _Pragma("unroll") for (int n = 0; n < 2; ++n) _Pragma("unroll") for (int k = 0; k < 2; ++k) \
;         acc[ai][bj][m][n] = __builtin_amdgcn_mfma_f32_16x16x32_bf16(Bt[n][k], At[m][k], acc[ai][bj][m][n], 0, 0, 0); __builtin_amdgcn_s_setprio(0); } while (0)
; #define PG8_WAIT_V(n) asm volatile("s_waitcnt vmcnt(" #n ")" ::: "memory")
; #define PG8_WAIT_L(n) asm volatile("s_waitcnt lgkmcnt(" #n ")" ::: "memory")
; #define PG8_BAR __builtin_amdgcn_s_barrier()
; template <class Epi, class Sched, bool ALIGN_EPI = false, bool SP2 = false>
; __device__ __forceinline__ void gemm_phase(PG8_LAS unsigned char* lds, const Gemm g, const Sched& S, const Epi& E) {
;     ...
;         const char* nA = has_next ? (const char*)g.A + (size_t)nxt.pm * tstepA + (size_t)nxt.pn * apn : cA; const char* nB = has_next ? (const char*)g.Bt + (size_t)nxt.pn * tstepB : cB;
;         for (int t = 0; t < nt; t += 2) {
;             const bool last = (t == nt - 2);
;             const char* a1 = cA + (size_t)(t + 1) * kstep;
;             const char* a2 = last ? nA : cA + (size_t)(t + 2) * kstep; const char* b2 = last ? nB : cB + (size_t)(t + 2) * kstep;
;             const char* a3 = a2 + kstep; const char* b3 = b2 + kstep;
;             if (last && has_next) S.a_ready(nxt);
;             if constexpr (SP2) {
;             PG8_LDB(B0, 0, 0); PG8_LDB(B1, 0, 1); PG8_SCHED; PG8_LDA(At, 0, 0); PG8_STAGE(PG8_SA(1, 1), a1 + hstepA, voffA);
;             PG8_WAIT_V(8); PG8_WAIT_L(0); PG8_BAR; PG8_MMA(0, 0, At, B0); PG8_MMA(0, 1, At, B1); PG8_BAR; PG8_SCHED;
.LBB0_368:
	s_ashr_i32 s17, s16, 31
	s_lshl_b64 s[18:19], s[16:17], 19
	s_add_u32 s18, s33, s18
	s_addc_u32 s19, s36, s19
	s_and_b64 s[24:25], s[4:5], exec
	s_cselect_b32 s17, s19, s21
	s_cselect_b32 s24, s18, s20
	s_ashr_i32 s15, s14, 31
	s_lshl_b64 s[26:27], s[14:15], 19
	s_add_u32 s40, s64, s26
	s_addc_u32 s41, s65, s27
	s_and_b64 s[26:27], s[4:5], exec
	s_cselect_b32 s15, s41, s23
	s_cselect_b32 s25, s40, s22
	s_add_u32 s20, s20, 0x40080
	s_addc_u32 s21, s21, 0
	s_add_u32 s26, s22, 0x100
	s_addc_u32 s27, s23, 0
	s_mov_b32 s28, -2
	ds_read_b128 v[162:165], v159
	ds_read_b128 v[166:169], v159 offset:1024
	ds_read_b128 v[170:173], v159 offset:2048
	ds_read_b128 v[174:177], v159 offset:3072
	ds_read_b128 v[178:181], v160
	ds_read_b128 v[182:185], v160 offset:1024
	ds_read_b128 v[186:189], v160 offset:2048
	ds_read_b128 v[190:193], v160 offset:3072
	s_add_u32 s22, s20, 0xfffc0080
	s_addc_u32 s23, s21, -1
	s_cmp_eq_u32 s28, 12
	s_cselect_b32 s35, s17, s23
	s_cselect_b32 s34, s24, s22
	s_cselect_b32 s23, s15, s27
	s_cselect_b32 s22, s25, s26
	v_lshl_add_u64 v[226:227], s[20:21], 0, v[138:139]
	s_add_i32 m0, s44, 0xc000
	ds_read_b128 v[194:197], v161
	ds_read_b128 v[198:201], v161 offset:1024
	ds_read_b128 v[202:205], v161 offset:2048
	ds_read_b128 v[206:209], v161 offset:3072
	ds_read_b128 v[210:213], v161 offset:4096
	ds_read_b128 v[214:217], v161 offset:5120
	ds_read_b128 v[218:221], v161 offset:6144
	ds_read_b128 v[222:225], v161 offset:7168
	global_load_lds_dwordx4 v[226:227], off
	v_lshl_add_u64 v[226:227], s[20:21], 0, v[140:141]
	s_add_i32 m0, s44, 0xe000
	s_nop 0
	global_load_lds_dwordx4 v[226:227], off
	s_cmp_lg_u32 s99, 0
	s_cbranch_scc1 .Lrw_P3_0r
	s_waitcnt vmcnt(8)
	s_branch .Lrw_P3_0d

; #define PG8_STAGE(bufoff, gbase, voff) do { _Pragma("unroll") for (int _i = 0; _i < 2; ++_i) \
;         __builtin_amdgcn_global_load_lds((const unsigned*)((const char*)(gbase) + (voff)[_i]), (PG8_LAS unsigned*)(lds + (bufoff) + ldsw + _i * 8192), 16, 0, PG8_LOAD_AUX); } while (0)
; #define PG8_LDA(dst, b, h) do { _Pragma("unroll") for (int m = 0; m < 4; ++m) _Pragma("unroll") for (int k = 0; k < 2; ++k) dst[m][k] = *(const PG8_LAS bf16x8*)(lds + PG8_SA(b, h) + aoff + m * 2048 + k * 1024); } while (0)
; #define PG8_MMA(ai, bj, At, Bt) do { __builtin_amdgcn_s_setprio(1); _Pragma("unroll") for (int m = 0; m < 4; ++m) _Pragma("unroll") for (int n = 0; n < 2; ++n) _Pragma("unroll") for (int k = 0; k < 2; ++k) \
;         acc[ai][bj][m][n] = __builtin_amdgcn_mfma_f32_16x16x32_bf16(Bt[n][k], At[m][k], acc[ai][bj][m][n], 0, 0, 0); __builtin_amdgcn_s_setprio(0); } while (0)
; #define PG8_WAIT_V(n) asm volatile("s_waitcnt vmcnt(" #n ")" ::: "memory")
; #define PG8_WAIT_L(n) asm volatile("s_waitcnt lgkmcnt(" #n ")" ::: "memory")
; #define PG8_BAR __builtin_amdgcn_s_barrier()
; #define PG8_SCHED __builtin_amdgcn_sched_barrier(0)
; template <class Epi, class Sched, bool ALIGN_EPI = false, bool SP2 = false>
; __device__ __forceinline__ void gemm_phase(PG8_LAS unsigned char* lds, const Gemm g, const Sched& S, const Epi& E) {
;     ...
;             PG8_WAIT_V(8); PG8_WAIT_L(0); PG8_BAR; PG8_MMA(0, 0, At, B0); PG8_MMA(0, 1, At, B1); PG8_BAR; PG8_SCHED;
;             PG8_LDA(At, 0, 1); PG8_STAGE(PG8_SB(0, 0), b2, voffB); PG8_STAGE(PG8_SB(0, 1), b2 + hstepB, voffB); PG8_STAGE(PG8_SA(0, 0), a2, voffA);
;             PG8_WAIT_V(8); PG8_WAIT_L(0); PG8_BAR; PG8_MMA(1, 0, At, B0); PG8_MMA(1, 1, At, B1); PG8_BAR; PG8_SCHED;
.Lrw_P3_0d:
	s_waitcnt lgkmcnt(0)
	s_barrier
	s_setprio 1
	s_waitcnt lgkmcnt(0)
	v_mfma_f32_16x16x32_bf16 v[124:127], v[162:165], v[194:197], 0
	v_mfma_f32_16x16x32_bf16 v[120:123], v[170:173], v[194:197], 0
	v_mfma_f32_16x16x32_bf16 v[108:111], v[162:165], v[202:205], 0
	v_mfma_f32_16x16x32_bf16 v[104:107], v[170:173], v[202:205], 0
	v_mfma_f32_16x16x32_bf16 v[92:95], v[162:165], v[210:213], 0
	v_mfma_f32_16x16x32_bf16 v[88:91], v[170:173], v[210:213], 0
	v_mfma_f32_16x16x32_bf16 v[76:79], v[162:165], v[218:221], 0
	v_mfma_f32_16x16x32_bf16 v[72:75], v[170:173], v[218:221], 0
	v_mfma_f32_16x16x32_bf16 v[124:127], v[166:169], v[198:201], v[124:127]
	v_mfma_f32_16x16x32_bf16 v[120:123], v[174:177], v[198:201], v[120:123]
	v_mfma_f32_16x16x32_bf16 v[108:111], v[166:169], v[206:209], v[108:111]
	v_mfma_f32_16x16x32_bf16 v[104:107], v[174:177], v[206:209], v[104:107]
	v_mfma_f32_16x16x32_bf16 v[92:95], v[166:169], v[214:217], v[92:95]
	v_mfma_f32_16x16x32_bf16 v[88:91], v[174:177], v[214:217], v[88:91]
	v_mfma_f32_16x16x32_bf16 v[76:79], v[166:169], v[222:225], v[76:79]
	v_mfma_f32_16x16x32_bf16 v[72:75], v[174:177], v[222:225], v[72:75]
	s_setprio 0
	s_setprio 1
	v_mfma_f32_16x16x32_bf16 v[116:119], v[178:181], v[194:197], 0
	v_mfma_f32_16x16x32_bf16 v[112:115], v[186:189], v[194:197], 0
	v_mfma_f32_16x16x32_bf16 v[100:103], v[178:181], v[202:205], 0
	v_mfma_f32_16x16x32_bf16 v[96:99], v[186:189], v[202:205], 0
	v_mfma_f32_16x16x32_bf16 v[84:87], v[178:181], v[210:213], 0
	v_mfma_f32_16x16x32_bf16 v[80:83], v[186:189], v[210:213], 0
	v_mfma_f32_16x16x32_bf16 v[68:71], v[178:181], v[218:221], 0
	v_mfma_f32_16x16x32_bf16 v[64:67], v[186:189], v[218:221], 0
	v_mfma_f32_16x16x32_bf16 v[116:119], v[182:185], v[198:201], v[116:119]
	v_mfma_f32_16x16x32_bf16 v[112:115], v[190:193], v[198:201], v[112:115]
	v_mfma_f32_16x16x32_bf16 v[100:103], v[182:185], v[206:209], v[100:103]
	v_mfma_f32_16x16x32_bf16 v[96:99], v[190:193], v[206:209], v[96:99]
	v_mfma_f32_16x16x32_bf16 v[84:87], v[182:185], v[214:217], v[84:87]
	v_mfma_f32_16x16x32_bf16 v[80:83], v[190:193], v[214:217], v[80:83]
	v_mfma_f32_16x16x32_bf16 v[68:71], v[182:185], v[222:225], v[68:71]
	v_mfma_f32_16x16x32_bf16 v[64:67], v[190:193], v[222:225], v[64:67]
	s_setprio 0
	s_barrier
	s_add_i32 s29, s53, s37
	v_lshl_add_u64 v[226:227], s[22:23], 0, v[132:133]
	s_mov_b32 m0, s29
	ds_read_b128 v[194:197], v161 offset:16384
	ds_read_b128 v[198:201], v161 offset:17408
	ds_read_b128 v[202:205], v161 offset:18432
	ds_read_b128 v[206:209], v161 offset:19456
	ds_read_b128 v[210:213], v161 offset:20480
	ds_read_b128 v[214:217], v161 offset:21504
	ds_read_b128 v[218:221], v161 offset:22528
	ds_read_b128 v[222:225], v161 offset:23552
	global_load_lds_dwordx4 v[226:227], off
	s_add_i32 m0, s29, 0x2000
	s_add_u32 s30, s22, 0x10000
	v_lshl_add_u64 v[228:229], s[22:23], 0, v[128:129]
	s_addc_u32 s31, s23, 0
	s_add_i32 s29, s54, s37
	global_load_lds_dwordx4 v[228:229], off
	v_lshl_add_u64 v[230:231], s[30:31], 0, v[132:133]
	s_mov_b32 m0, s29
	v_lshl_add_u64 v[232:233], s[34:35], 0, v[130:131]
	global_load_lds_dwordx4 v[230:231], off
	v_lshl_add_u64 v[230:231], s[30:31], 0, v[128:129]
	s_add_i32 m0, s29, 0x2000
	s_nop 0
	global_load_lds_dwordx4 v[230:231], off
	v_lshl_add_u64 v[230:231], s[34:35], 0, v[134:135]
	s_mov_b32 m0, s44
	s_nop 0
	global_load_lds_dwordx4 v[230:231], off
	s_mov_b32 m0, s45
	s_nop 0
	global_load_lds_dwordx4 v[232:233], off
	s_cmp_lg_u32 s99, 0
	s_cbranch_scc1 .Lrw_P3_1r
	s_waitcnt vmcnt(8)
	s_branch .Lrw_P3_1d

; #define PG8_STAGE(bufoff, gbase, voff) do { _Pragma("unroll") for (int _i = 0; _i < 2; ++_i) \
;         __builtin_amdgcn_global_load_lds((const unsigned*)((const char*)(gbase) + (voff)[_i]), (PG8_LAS unsigned*)(lds + (bufoff) + ldsw + _i * 8192), 16, 0, PG8_LOAD_AUX); } while (0)
; #define PG8_LDA(dst, b, h) do { _Pragma("unroll") for (int m = 0; m < 4; ++m) _Pragma("unroll") for (int k = 0; k < 2; ++k) dst[m][k] = *(const PG8_LAS bf16x8*)(lds + PG8_SA(b, h) + aoff + m * 2048 + k * 1024); } while (0)
; #define PG8_LDB(dst, b, h) do { _Pragma("unroll") for (int n = 0; n < 2; ++n) _Pragma("unroll") for (int k = 0; k < 2; ++k) dst[n][k] = *(const PG8_LAS bf16x8*)(lds + PG8_SB(b, h) + boff + n * 2048 + k * 1024); } while (0)
; #define PG8_MMA(ai, bj, At, Bt) do { __builtin_amdgcn_s_setprio(1); _Pragma("unroll") for (int m = 0; m < 4; ++m) _Pragma("unroll") for (int n = 0; n < 2; ++n) _Pragma("unroll") for (int k = 0; k < 2; ++k) \
;         acc[ai][bj][m][n] = __builtin_amdgcn_mfma_f32_16x16x32_bf16(Bt[n][k], At[m][k], acc[ai][bj][m][n], 0, 0, 0); __builtin_amdgcn_s_setprio(0); } while (0)
; #define PG8_WAIT_V(n) asm volatile("s_waitcnt vmcnt(" #n ")" ::: "memory")
; #define PG8_WAIT_L(n) asm volatile("s_waitcnt lgkmcnt(" #n ")" ::: "memory")
; #define PG8_BAR __builtin_amdgcn_s_barrier()
; #define PG8_SCHED __builtin_amdgcn_sched_barrier(0)
; template <class Epi, class Sched, bool ALIGN_EPI = false, bool SP2 = false>
; __device__ __forceinline__ void gemm_phase(PG8_LAS unsigned char* lds, const Gemm g, const Sched& S, const Epi& E) {
;     ...
;             PG8_LDB(B0, 1, 0); PG8_LDB(B1, 1, 1); PG8_SCHED; PG8_LDA(At, 1, 0); PG8_STAGE(PG8_SA(0, 1), a2 + hstepA, voffA);
;             PG8_WAIT_V(8); PG8_WAIT_L(0); PG8_BAR; PG8_MMA(0, 0, At, B0); PG8_MMA(0, 1, At, B1); PG8_BAR; PG8_SCHED;
.Lkmid_P3:
	s_add_i32 s29, 0, 0x18000
	s_add_i32 s38, 0, 0x1c000
	v_add_u32_e32 v174, s29, v146
	v_add_u32_e32 v190, s38, v146
	ds_read_b128 v[162:165], v174
	ds_read_b128 v[166:169], v174 offset:1024
	ds_read_b128 v[170:173], v174 offset:2048
	ds_read_b128 v[174:177], v174 offset:3072
	ds_read_b128 v[178:181], v190
	ds_read_b128 v[182:185], v190 offset:1024
	ds_read_b128 v[186:189], v190 offset:2048
	ds_read_b128 v[190:193], v190 offset:3072
	s_add_u32 s30, s34, 0x40000
	s_addc_u32 s31, s35, 0
	s_mov_b32 m0, s46
	v_lshl_add_u64 v[234:235], s[30:31], 0, v[134:135]
	ds_read_b128 v[194:197], v161 offset:32768
	ds_read_b128 v[198:201], v161 offset:33792
	ds_read_b128 v[202:205], v161 offset:34816
	ds_read_b128 v[206:209], v161 offset:35840
	ds_read_b128 v[210:213], v161 offset:36864
	ds_read_b128 v[214:217], v161 offset:37888
	ds_read_b128 v[218:221], v161 offset:38912
	ds_read_b128 v[222:225], v161 offset:39936
	global_load_lds_dwordx4 v[234:235], off
	v_lshl_add_u64 v[234:235], s[30:31], 0, v[130:131]
	s_mov_b32 m0, s47
	s_nop 0
	global_load_lds_dwordx4 v[234:235], off
	s_waitcnt vmcnt(8)
	s_waitcnt lgkmcnt(0)
	s_barrier
	s_setprio 1
	s_waitcnt lgkmcnt(0)
	v_mfma_f32_16x16x32_bf16 v[124:127], v[162:165], v[194:197], v[124:127]
	v_mfma_f32_16x16x32_bf16 v[120:123], v[170:173], v[194:197], v[120:123]
	v_mfma_f32_16x16x32_bf16 v[108:111], v[162:165], v[202:205], v[108:111]
	v_mfma_f32_16x16x32_bf16 v[104:107], v[170:173], v[202:205], v[104:107]
	v_mfma_f32_16x16x32_bf16 v[92:95], v[162:165], v[210:213], v[92:95]
	v_mfma_f32_16x16x32_bf16 v[88:91], v[170:173], v[210:213], v[88:91]
	v_mfma_f32_16x16x32_bf16 v[76:79], v[162:165], v[218:221], v[76:79]
	v_mfma_f32_16x16x32_bf16 v[72:75], v[170:173], v[218:221], v[72:75]
	v_mfma_f32_16x16x32_bf16 v[124:127], v[166:169], v[198:201], v[124:127]
	v_mfma_f32_16x16x32_bf16 v[120:123], v[174:177], v[198:201], v[120:123]
	v_mfma_f32_16x16x32_bf16 v[108:111], v[166:169], v[206:209], v[108:111]
	v_mfma_f32_16x16x32_bf16 v[104:107], v[174:177], v[206:209], v[104:107]
	v_mfma_f32_16x16x32_bf16 v[92:95], v[166:169], v[214:217], v[92:95]
	v_mfma_f32_16x16x32_bf16 v[88:91], v[174:177], v[214:217], v[88:91]
	v_mfma_f32_16x16x32_bf16 v[76:79], v[166:169], v[222:225], v[76:79]
	v_mfma_f32_16x16x32_bf16 v[72:75], v[174:177], v[222:225], v[72:75]
	s_setprio 0
	s_setprio 1
	v_mfma_f32_16x16x32_bf16 v[116:119], v[178:181], v[194:197], v[116:119]
	v_mfma_f32_16x16x32_bf16 v[112:115], v[186:189], v[194:197], v[112:115]
	v_mfma_f32_16x16x32_bf16 v[100:103], v[178:181], v[202:205], v[100:103]
	v_mfma_f32_16x16x32_bf16 v[96:99], v[186:189], v[202:205], v[96:99]
	v_mfma_f32_16x16x32_bf16 v[84:87], v[178:181], v[210:213], v[84:87]
	v_mfma_f32_16x16x32_bf16 v[80:83], v[186:189], v[210:213], v[80:83]
	v_mfma_f32_16x16x32_bf16 v[68:71], v[178:181], v[218:221], v[68:71]
	v_mfma_f32_16x16x32_bf16 v[64:67], v[186:189], v[218:221], v[64:67]
	v_mfma_f32_16x16x32_bf16 v[116:119], v[182:185], v[198:201], v[116:119]
	v_mfma_f32_16x16x32_bf16 v[112:115], v[190:193], v[198:201], v[112:115]
	v_mfma_f32_16x16x32_bf16 v[100:103], v[182:185], v[206:209], v[100:103]
	v_mfma_f32_16x16x32_bf16 v[96:99], v[190:193], v[206:209], v[96:99]
	v_mfma_f32_16x16x32_bf16 v[84:87], v[182:185], v[214:217], v[84:87]
	v_mfma_f32_16x16x32_bf16 v[80:83], v[190:193], v[214:217], v[80:83]
	v_mfma_f32_16x16x32_bf16 v[68:71], v[182:185], v[222:225], v[68:71]
	v_mfma_f32_16x16x32_bf16 v[64:67], v[190:193], v[222:225], v[64:67]
	s_setprio 0
	s_barrier
; #define PG8_STAGE(bufoff, gbase, voff) do { _Pragma("unroll") for (int _i = 0; _i < 2; ++_i) \
;         __builtin_amdgcn_global_load_lds((const unsigned*)((const char*)(gbase) + (voff)[_i]), (PG8_LAS unsigned*)(lds + (bufoff) + ldsw + _i * 8192), 16, 0, PG8_LOAD_AUX); } while (0)
; #define PG8_LDA(dst, b, h) do { _Pragma("unroll") for (int m = 0; m < 4; ++m) _Pragma("unroll") for (int k = 0; k < 2; ++k) dst[m][k] = *(const PG8_LAS bf16x8*)(lds + PG8_SA(b, h) + aoff + m * 2048 + k * 1024); } while (0)
; #define PG8_MMA(ai, bj, At, Bt) do { __builtin_amdgcn_s_setprio(1); _Pragma("unroll") for (int m = 0; m < 4; ++m) _Pragma("unroll") for (int n = 0; n < 2; ++n) _Pragma("unroll") for (int k = 0; k < 2; ++k) \
;         acc[ai][bj][m][n] = __builtin_amdgcn_mfma_f32_16x16x32_bf16(Bt[n][k], At[m][k], acc[ai][bj][m][n], 0, 0, 0); __builtin_amdgcn_s_setprio(0); } while (0)
; #define PG8_WAIT_V(n) asm volatile("s_waitcnt vmcnt(" #n ")" ::: "memory")
; #define PG8_WAIT_L(n) asm volatile("s_waitcnt lgkmcnt(" #n ")" ::: "memory")
; #define PG8_BAR __builtin_amdgcn_s_barrier()
; #define PG8_SCHED __builtin_amdgcn_sched_barrier(0)
; template <class Epi, class Sched, bool ALIGN_EPI = false, bool SP2 = false>
; __device__ __forceinline__ void gemm_phase(PG8_LAS unsigned char* lds, const Gemm g, const Sched& S, const Epi& E) {
;     ...
;             PG8_LDA(At, 1, 1); PG8_STAGE(PG8_SB(1, 0), b3, voffB); PG8_STAGE(PG8_SB(1, 1), b3 + hstepB, voffB); PG8_STAGE(PG8_SA(1, 0), a3, voffA);
;             PG8_WAIT_V(8); PG8_WAIT_L(0); PG8_BAR; PG8_MMA(1, 0, At, B0); PG8_MMA(1, 1, At, B1); PG8_BAR; PG8_SCHED;
;     ...
;         if constexpr (ALIGN_EPI) { if (wr == 0) PG8_BAR; }
	s_add_i32 s29, s29, s37
	v_lshl_add_u64 v[226:227], v[226:227], 0, s[10:11]
	s_mov_b32 m0, s29
	ds_read_b128 v[194:197], v161 offset:49152
	ds_read_b128 v[198:201], v161 offset:50176
	ds_read_b128 v[202:205], v161 offset:51200
	ds_read_b128 v[206:209], v161 offset:52224
	ds_read_b128 v[210:213], v161 offset:53248
	ds_read_b128 v[214:217], v161 offset:54272
	ds_read_b128 v[218:221], v161 offset:55296
	ds_read_b128 v[222:225], v161 offset:56320
	global_load_lds_dwordx4 v[226:227], off
	s_add_i32 m0, s29, 0x2000
	s_add_u32 s22, s22, 0x10080
	v_lshl_add_u64 v[226:227], v[228:229], 0, s[10:11]
	s_addc_u32 s23, s23, 0
	s_add_i32 s29, s38, s37
	global_load_lds_dwordx4 v[226:227], off
	v_lshl_add_u64 v[226:227], s[22:23], 0, v[132:133]
	s_mov_b32 m0, s29
	s_nop 0
	global_load_lds_dwordx4 v[226:227], off
	v_lshl_add_u64 v[226:227], s[22:23], 0, v[128:129]
	s_add_i32 m0, s29, 0x2000
	s_nop 0
	global_load_lds_dwordx4 v[226:227], off
	v_lshl_add_u64 v[226:227], v[230:231], 0, s[10:11]
	s_mov_b32 m0, s49
	s_nop 0
	global_load_lds_dwordx4 v[226:227], off
	v_lshl_add_u64 v[226:227], v[232:233], 0, s[10:11]
	s_mov_b32 m0, s50
	s_nop 0
	global_load_lds_dwordx4 v[226:227], off
	s_waitcnt vmcnt(8)
	s_waitcnt lgkmcnt(0)
	s_barrier
	s_setprio 1
	s_waitcnt lgkmcnt(0)
	v_mfma_f32_16x16x32_bf16 v[60:63], v[162:165], v[194:197], v[60:63]
	v_mfma_f32_16x16x32_bf16 v[56:59], v[170:173], v[194:197], v[56:59]
	v_mfma_f32_16x16x32_bf16 v[44:47], v[162:165], v[202:205], v[44:47]
	v_mfma_f32_16x16x32_bf16 v[40:43], v[170:173], v[202:205], v[40:43]
	v_mfma_f32_16x16x32_bf16 v[28:31], v[162:165], v[210:213], v[28:31]
	v_mfma_f32_16x16x32_bf16 v[24:27], v[170:173], v[210:213], v[24:27]
	v_mfma_f32_16x16x32_bf16 v[12:15], v[162:165], v[218:221], v[12:15]
	v_mfma_f32_16x16x32_bf16 v[8:11], v[170:173], v[218:221], v[8:11]
	v_mfma_f32_16x16x32_bf16 v[60:63], v[166:169], v[198:201], v[60:63]
	v_mfma_f32_16x16x32_bf16 v[56:59], v[174:177], v[198:201], v[56:59]
	v_mfma_f32_16x16x32_bf16 v[44:47], v[166:169], v[206:209], v[44:47]
	v_mfma_f32_16x16x32_bf16 v[40:43], v[174:177], v[206:209], v[40:43]
	v_mfma_f32_16x16x32_bf16 v[28:31], v[166:169], v[214:217], v[28:31]
	v_mfma_f32_16x16x32_bf16 v[24:27], v[174:177], v[214:217], v[24:27]
	v_mfma_f32_16x16x32_bf16 v[12:15], v[166:169], v[222:225], v[12:15]
	v_mfma_f32_16x16x32_bf16 v[8:11], v[174:177], v[222:225], v[8:11]
	s_setprio 0
	s_setprio 1
	v_mfma_f32_16x16x32_bf16 v[52:55], v[178:181], v[194:197], v[52:55]
	v_mfma_f32_16x16x32_bf16 v[48:51], v[186:189], v[194:197], v[48:51]
	v_mfma_f32_16x16x32_bf16 v[36:39], v[178:181], v[202:205], v[36:39]
	v_mfma_f32_16x16x32_bf16 v[32:35], v[186:189], v[202:205], v[32:35]
	v_mfma_f32_16x16x32_bf16 v[20:23], v[178:181], v[210:213], v[20:23]
	v_mfma_f32_16x16x32_bf16 v[16:19], v[186:189], v[210:213], v[16:19]
	v_mfma_f32_16x16x32_bf16 v[4:7], v[178:181], v[218:221], v[4:7]
	v_mfma_f32_16x16x32_bf16 v[0:3], v[186:189], v[218:221], v[0:3]
	v_mfma_f32_16x16x32_bf16 v[52:55], v[182:185], v[198:201], v[52:55]
	v_mfma_f32_16x16x32_bf16 v[48:51], v[190:193], v[198:201], v[48:51]
	v_mfma_f32_16x16x32_bf16 v[36:39], v[182:185], v[206:209], v[36:39]
	v_mfma_f32_16x16x32_bf16 v[32:35], v[190:193], v[206:209], v[32:35]
	v_mfma_f32_16x16x32_bf16 v[20:23], v[182:185], v[214:217], v[20:23]
	v_mfma_f32_16x16x32_bf16 v[16:19], v[190:193], v[214:217], v[16:19]
	v_mfma_f32_16x16x32_bf16 v[4:7], v[182:185], v[222:225], v[4:7]
	v_mfma_f32_16x16x32_bf16 v[0:3], v[190:193], v[222:225], v[0:3]
	s_setprio 0
	s_barrier
	s_add_i32 s28, s28, 2
	s_add_u32 s20, s20, 0x100
	s_addc_u32 s21, s21, 0
	s_add_u32 s26, s26, 0x100
	s_addc_u32 s27, s27, 0
	s_cmp_gt_u32 s28, 13
	s_cbranch_scc0 .LBB0_369
	s_mov_b32 s99, 1
	s_and_b64 vcc, exec, s[12:13]
	s_cbranch_vccz .LBB0_372
	s_barrier

; #define PG8_STAGE(bufoff, gbase, voff) do { _Pragma("unroll") for (int _i = 0; _i < 2; ++_i) \
;         __builtin_amdgcn_global_load_lds((const unsigned*)((const char*)(gbase) + (voff)[_i]), (PG8_LAS unsigned*)(lds + (bufoff) + ldsw + _i * 8192), 16, 0, PG8_LOAD_AUX); } while (0)
; #define PG8_WAIT_V(n) asm volatile("s_waitcnt vmcnt(" #n ")" ::: "memory")
; #define PG8_BAR __builtin_amdgcn_s_barrier()
; template <class Epi, class Sched, bool ALIGN_EPI = false, bool SP2 = false>
; __device__ __forceinline__ void gemm_phase(PG8_LAS unsigned char* lds, const Gemm g, const Sched& S, const Epi& E) {
;     ...
;     for (int i = 0; i < 2; ++i) { int R, C; stage_rc(tid * 16 + i * 8192, R, C); const int Rb = Epi::WIDE ? (64 * (R >> 5) + perm32(R & 31)) : (Epi::PERM ? ((R & ~31) + perm32(R & 31)) : R);
;         voffA[i] = (unsigned)(R * lda + C) * 2u; voffB[i] = (unsigned)(Rb * K + C) * 2u; }
;     const size_t kstep = (size_t)(BK * 2);
;     const size_t hstepA = (size_t)HALF * lda * 2, hstepB = (size_t)(Epi::WIDE ? 32 : HALF) * K * 2;
;     const size_t tstepA = 2 * hstepA, tstepB = (size_t)BM * K * 2;
;     const size_t apn = (size_t)g.a_pn_off * 2;
;     const unsigned ldsw = (unsigned)wid * 1024u;
;     const int aoff = lds_byte(wr * 64 + fr, fq * 8), boff = lds_byte(wc * 32 + fr, fq * 8);
;     ...
;         PG8_WAIT_V(2); PG8_BAR;
;         PG8_STAGE(PG8_SB(1, 0), cB + kstep, voffB); PG8_STAGE(PG8_SA(1, 0), cA + kstep, voffA); PG8_STAGE(PG8_SB(1, 1), cB + hstepB + kstep, voffB);
;         PG8_WAIT_V(6); PG8_BAR;
.LBB0_666:
	s_lshl_b32 s1, s8, 5
	s_mov_b64 s[8:9], 0x80
	s_and_b32 s16, s1, 0x60
	s_add_i32 m0, s43, 0x18000
	v_lshl_add_u64 v[6:7], v[6:7], 0, s[8:9]
	s_ashr_i32 s50, s86, 31
	s_lshl_b32 s13, s12, 13
	s_lshl_b32 s17, s16, 7
	s_waitcnt vmcnt(2)
	s_barrier
	global_load_lds_dwordx4 v[6:7], off
	v_lshl_add_u64 v[4:5], v[4:5], 0, s[8:9]
	s_add_i32 m0, s43, 0x1a000
	s_add_i32 s51, s43, 0x8000
	s_add_i32 s52, s43, 0xa000
	global_load_lds_dwordx4 v[4:5], off
	v_lshl_add_u64 v[0:1], v[0:1], 0, s[8:9]
	s_mov_b32 m0, s51
	s_add_u32 s14, s22, 0x40080
	global_load_lds_dwordx4 v[0:1], off
	v_lshl_add_u64 v[0:1], v[2:3], 0, s[8:9]
	s_mov_b32 m0, s52
	s_addc_u32 s15, s23, 0
	global_load_lds_dwordx4 v[0:1], off
	s_add_i32 m0, s43, 0x1c000
	v_lshl_add_u64 v[0:1], s[14:15], 0, v[130:131]
	global_load_lds_dwordx4 v[0:1], off
	v_lshl_add_u64 v[0:1], s[14:15], 0, v[134:135]
	s_add_i32 m0, s43, 0x1e000
	v_bfe_u32 v3, v154, 4, 2
	global_load_lds_dwordx4 v[0:1], off
	s_sext_i32_i8 s1, s2
	v_lshlrev_b32_e32 v0, 4, v3
	v_lshlrev_b32_e32 v1, 6, v154
	s_movk_i32 s2, 0x3c0
	v_and_or_b32 v4, v1, s2, v0
	v_lshlrev_b32_e32 v1, 2, v154
	v_and_b32_e32 v5, 32, v1
	v_mov_b32_e32 v1, v131
	v_and_b32_e32 v2, 15, v154
	v_lshl_add_u64 v[136:137], s[82:83], 0, v[0:1]
	v_lshlrev_b32_e32 v1, 8, v154
	v_lshl_or_b32 v152, s12, 6, v2
	v_lshl_or_b32 v0, v2, 6, v0
	v_and_b32_e32 v1, 0x38000, v1
	v_lshlrev_b32_e32 v2, 11, v10
	v_or3_b32 v1, v8, v1, v2
	v_add_u32_e32 v138, v1, v9
	v_lshlrev_b32_e32 v1, 4, v11
	v_bitop3_b32 v0, v0, s13, v5 bitop3:0xde
	s_waitcnt vmcnt(6)
	s_cmpk_lt_u32 s3, 0x100
	v_and_b32_e32 v1, 0x78000, v1
	v_bitop3_b32 v156, s17, v4, v5 bitop3:0xf6
	s_cselect_b64 s[12:13], -1, 0
	v_or3_b32 v1, v8, v1, v2
	s_add_i32 s54, 0, 0x10000
	s_add_i32 s55, 0, 0x14000
	v_add_u32_e32 v160, 0, v0
	v_mbcnt_lo_u32_b32 v0, -1, 0
	s_mov_b32 s53, s86
	v_lshl_or_b32 v157, v3, 3, s16
	v_mov_b32_e32 v139, v131
	v_add_u32_e32 v140, v1, v9
	v_mov_b32_e32 v141, v131
	v_mov_b64_e32 v[142:143], 0xb00
	v_mov_b64_e32 v[144:145], 0xaff
	v_add_u32_e32 v158, s54, v156
	v_add_u32_e32 v159, s55, v156
	v_mbcnt_hi_u32_b32 v161, -1, v0
	v_mov_b32_e32 v162, 0x358637bd
	s_movk_i32 s56, 0x1600
	s_barrier
	s_mov_b32 s99, 0
	s_branch .LBB0_669

; #define PG8_STAGE(bufoff, gbase, voff) do { _Pragma("unroll") for (int _i = 0; _i < 2; ++_i) \
;         __builtin_amdgcn_global_load_lds((const unsigned*)((const char*)(gbase) + (voff)[_i]), (PG8_LAS unsigned*)(lds + (bufoff) + ldsw + _i * 8192), 16, 0, PG8_LOAD_AUX); } while (0)
; #define PG8_LDA(dst, b, h) do { _Pragma("unroll") for (int m = 0; m < 4; ++m) _Pragma("unroll") for (int k = 0; k < 2; ++k) dst[m][k] = *(const PG8_LAS bf16x8*)(lds + PG8_SA(b, h) + aoff + m * 2048 + k * 1024); } while (0)
; #define PG8_LDB(dst, b, h) do { _Pragma("unroll") for (int n = 0; n < 2; ++n) _Pragma("unroll") for (int k = 0; k < 2; ++k) dst[n][k] = *(const PG8_LAS bf16x8*)(lds + PG8_SB(b, h) + boff + n * 2048 + k * 1024); } while (0)
; #define PG8_WAIT_V(n) asm volatile("s_waitcnt vmcnt(" #n ")" ::: "memory")
; #define PG8_WAIT_L(n) asm volatile("s_waitcnt lgkmcnt(" #n ")" ::: "memory")
; #define PG8_BAR __builtin_amdgcn_s_barrier()
; #define PG8_SCHED __builtin_amdgcn_sched_barrier(0)
; template <class Epi, class Sched, bool ALIGN_EPI = false, bool SP2 = false>
; __device__ __forceinline__ void gemm_phase(PG8_LAS unsigned char* lds, const Gemm g, const Sched& S, const Epi& E) {
;     ...
;         const char* nA = has_next ? (const char*)g.A + (size_t)nxt.pm * tstepA + (size_t)nxt.pn * apn : cA; const char* nB = has_next ? (const char*)g.Bt + (size_t)nxt.pn * tstepB : cB;
;         for (int t = 0; t < nt; t += 2) {
;             const bool last = (t == nt - 2);
;             const char* a1 = cA + (size_t)(t + 1) * kstep;
;             const char* a2 = last ? nA : cA + (size_t)(t + 2) * kstep; const char* b2 = last ? nB : cB + (size_t)(t + 2) * kstep;
;             const char* a3 = a2 + kstep; const char* b3 = b2 + kstep;
;             if (last && has_next) S.a_ready(nxt);
;             if constexpr (SP2) {
;             PG8_LDB(B0, 0, 0); PG8_LDB(B1, 0, 1); PG8_SCHED; PG8_LDA(At, 0, 0); PG8_STAGE(PG8_SA(1, 1), a1 + hstepA, voffA);
;             PG8_WAIT_V(8); PG8_WAIT_L(0); PG8_BAR; PG8_MMA(0, 0, At, B0); PG8_MMA(0, 1, At, B1); PG8_BAR; PG8_SCHED;
;             PG8_LDA(At, 0, 1); PG8_STAGE(PG8_SB(0, 0), b2, voffB); PG8_STAGE(PG8_SB(0, 1), b2 + hstepB, voffB); PG8_STAGE(PG8_SA(0, 0), a2, voffA);
;             PG8_WAIT_V(8); PG8_WAIT_L(0); PG8_BAR; PG8_MMA(1, 0, At, B0); PG8_MMA(1, 1, At, B1); PG8_BAR; PG8_SCHED;
.LBB0_671:
	s_ashr_i32 s17, s16, 31
	s_lshl_b64 s[18:19], s[16:17], 19
	s_add_u32 s18, s30, s18
	s_addc_u32 s19, s31, s19
	s_and_b64 s[24:25], s[2:3], exec
	s_cselect_b32 s17, s19, s21
	s_cselect_b32 s24, s18, s20
	s_ashr_i32 s15, s14, 31
	s_lshl_b64 s[26:27], s[14:15], 19
	v_readlane_b32 s15, v239, 40
	s_add_u32 s36, s15, s26
	v_readlane_b32 s15, v239, 41
	s_addc_u32 s37, s15, s27
	s_and_b64 s[26:27], s[2:3], exec
	s_cselect_b32 s15, s37, s23
	s_cselect_b32 s25, s36, s22
	s_add_u32 s20, s20, 0x40080
	s_addc_u32 s21, s21, 0
	s_add_u32 s26, s22, 0x100
	s_addc_u32 s27, s23, 0
	s_mov_b32 s28, -2
	ds_read_b128 v[146:149], v158
	ds_read_b128 v[164:167], v158 offset:1024
	ds_read_b128 v[168:171], v158 offset:2048
	ds_read_b128 v[172:175], v158 offset:3072
	ds_read_b128 v[176:179], v159
	ds_read_b128 v[180:183], v159 offset:1024
	ds_read_b128 v[184:187], v159 offset:2048
	ds_read_b128 v[188:191], v159 offset:3072
	s_add_u32 s22, s20, 0xfffc0080
	s_addc_u32 s23, s21, -1
	s_cmp_eq_u32 s28, 12
	s_cselect_b32 s35, s17, s23
	s_cselect_b32 s34, s24, s22
	s_cselect_b32 s23, s15, s27
	s_cselect_b32 s22, s25, s26
	v_lshl_add_u64 v[150:151], s[20:21], 0, v[138:139]
	s_add_i32 m0, s43, 0xc000
	ds_read_b128 v[192:195], v160
	ds_read_b128 v[196:199], v160 offset:1024
	ds_read_b128 v[200:203], v160 offset:2048
	ds_read_b128 v[204:207], v160 offset:3072
	ds_read_b128 v[208:211], v160 offset:4096
	ds_read_b128 v[212:215], v160 offset:5120
	ds_read_b128 v[216:219], v160 offset:6144
	ds_read_b128 v[220:223], v160 offset:7168
	global_load_lds_dwordx4 v[150:151], off
	v_lshl_add_u64 v[150:151], s[20:21], 0, v[140:141]
	s_add_i32 m0, s43, 0xe000
	s_nop 0
	global_load_lds_dwordx4 v[150:151], off
	s_cmp_lg_u32 s99, 0
	s_cbranch_scc1 .Lrw_P7_0r
	s_waitcnt vmcnt(8)
	s_branch .Lrw_P7_0d
.Lrw_P7_0r:
	s_waitcnt vmcnt(16)
.Lrw_P7_0d:
	s_waitcnt lgkmcnt(0)
	s_barrier
	s_setprio 1
	s_waitcnt lgkmcnt(0)
	v_mfma_f32_16x16x32_bf16 v[124:127], v[146:149], v[192:195], 0
	v_mfma_f32_16x16x32_bf16 v[120:123], v[168:171], v[192:195], 0
	v_mfma_f32_16x16x32_bf16 v[108:111], v[146:149], v[200:203], 0
	v_mfma_f32_16x16x32_bf16 v[104:107], v[168:171], v[200:203], 0
	v_mfma_f32_16x16x32_bf16 v[92:95], v[146:149], v[208:211], 0
	v_mfma_f32_16x16x32_bf16 v[88:91], v[168:171], v[208:211], 0
	v_mfma_f32_16x16x32_bf16 v[76:79], v[146:149], v[216:219], 0
	v_mfma_f32_16x16x32_bf16 v[72:75], v[168:171], v[216:219], 0
	v_mfma_f32_16x16x32_bf16 v[124:127], v[164:167], v[196:199], v[124:127]
	v_mfma_f32_16x16x32_bf16 v[120:123], v[172:175], v[196:199], v[120:123]
	v_mfma_f32_16x16x32_bf16 v[108:111], v[164:167], v[204:207], v[108:111]
	v_mfma_f32_16x16x32_bf16 v[104:107], v[172:175], v[204:207], v[104:107]
	v_mfma_f32_16x16x32_bf16 v[92:95], v[164:167], v[212:215], v[92:95]
	v_mfma_f32_16x16x32_bf16 v[88:91], v[172:175], v[212:215], v[88:91]
	v_mfma_f32_16x16x32_bf16 v[76:79], v[164:167], v[220:223], v[76:79]
	v_mfma_f32_16x16x32_bf16 v[72:75], v[172:175], v[220:223], v[72:75]
	s_setprio 0
	s_setprio 1
	v_mfma_f32_16x16x32_bf16 v[116:119], v[176:179], v[192:195], 0
	v_mfma_f32_16x16x32_bf16 v[112:115], v[184:187], v[192:195], 0
	v_mfma_f32_16x16x32_bf16 v[100:103], v[176:179], v[200:203], 0
	v_mfma_f32_16x16x32_bf16 v[96:99], v[184:187], v[200:203], 0
	v_mfma_f32_16x16x32_bf16 v[84:87], v[176:179], v[208:211], 0
	v_mfma_f32_16x16x32_bf16 v[80:83], v[184:187], v[208:211], 0
	v_mfma_f32_16x16x32_bf16 v[68:71], v[176:179], v[216:219], 0
	v_mfma_f32_16x16x32_bf16 v[64:67], v[184:187], v[216:219], 0
	v_mfma_f32_16x16x32_bf16 v[116:119], v[180:183], v[196:199], v[116:119]
	v_mfma_f32_16x16x32_bf16 v[112:115], v[188:191], v[196:199], v[112:115]
	v_mfma_f32_16x16x32_bf16 v[100:103], v[180:183], v[204:207], v[100:103]
	v_mfma_f32_16x16x32_bf16 v[96:99], v[188:191], v[204:207], v[96:99]
	v_mfma_f32_16x16x32_bf16 v[84:87], v[180:183], v[212:215], v[84:87]
	v_mfma_f32_16x16x32_bf16 v[80:83], v[188:191], v[212:215], v[80:83]
	v_mfma_f32_16x16x32_bf16 v[68:71], v[180:183], v[220:223], v[68:71]
	v_mfma_f32_16x16x32_bf16 v[64:67], v[188:191], v[220:223], v[64:67]
	s_setprio 0
	s_barrier
	s_add_i32 s29, s54, s40
	v_lshl_add_u64 v[150:151], s[22:23], 0, v[130:131]
	s_mov_b32 m0, s29
	ds_read_b128 v[192:195], v160 offset:16384
	ds_read_b128 v[196:199], v160 offset:17408
	ds_read_b128 v[200:203], v160 offset:18432
	ds_read_b128 v[204:207], v160 offset:19456
	ds_read_b128 v[208:211], v160 offset:20480
	ds_read_b128 v[212:215], v160 offset:21504
	ds_read_b128 v[216:219], v160 offset:22528
	ds_read_b128 v[220:223], v160 offset:23552
	global_load_lds_dwordx4 v[150:151], off
	s_add_i32 m0, s29, 0x2000
	s_add_u32 s30, s22, 0x40000
	v_lshl_add_u64 v[224:225], s[22:23], 0, v[134:135]
	s_addc_u32 s31, s23, 0
	s_add_i32 s29, s55, s40
	global_load_lds_dwordx4 v[224:225], off
	v_lshl_add_u64 v[226:227], s[30:31], 0, v[130:131]
	s_mov_b32 m0, s29
	v_lshl_add_u64 v[228:229], s[34:35], 0, v[132:133]
	global_load_lds_dwordx4 v[226:227], off
	v_lshl_add_u64 v[226:227], s[30:31], 0, v[134:135]
	s_add_i32 m0, s29, 0x2000
	s_nop 0
	global_load_lds_dwordx4 v[226:227], off
	v_lshl_add_u64 v[226:227], s[34:35], 0, v[128:129]
	s_mov_b32 m0, s43
	s_nop 0
	global_load_lds_dwordx4 v[226:227], off
	s_mov_b32 m0, s46
	s_nop 0
	global_load_lds_dwordx4 v[228:229], off
	s_cmp_lg_u32 s99, 0
	s_cbranch_scc1 .Lrw_P7_1r
	s_waitcnt vmcnt(8)
	s_branch .Lrw_P7_1d

; #define PG8_MMA(ai, bj, At, Bt) do { __builtin_amdgcn_s_setprio(1); _Pragma("unroll") for (int m = 0; m < 4; ++m) _Pragma("unroll") for (int n = 0; n < 2; ++n) _Pragma("unroll") for (int k = 0; k < 2; ++k) \
;         acc[ai][bj][m][n] = __builtin_amdgcn_mfma_f32_16x16x32_bf16(Bt[n][k], At[m][k], acc[ai][bj][m][n], 0, 0, 0); __builtin_amdgcn_s_setprio(0); } while (0)
; #define PG8_WAIT_V(n) asm volatile("s_waitcnt vmcnt(" #n ")" ::: "memory")
; #define PG8_WAIT_L(n) asm volatile("s_waitcnt lgkmcnt(" #n ")" ::: "memory")
; #define PG8_BAR __builtin_amdgcn_s_barrier()
; #define PG8_SCHED __builtin_amdgcn_sched_barrier(0)
; template <class Epi, class Sched, bool ALIGN_EPI = false, bool SP2 = false>
; __device__ __forceinline__ void gemm_phase(PG8_LAS unsigned char* lds, const Gemm g, const Sched& S, const Epi& E) {
;     ...
;             PG8_WAIT_V(8); PG8_WAIT_L(0); PG8_BAR; PG8_MMA(1, 0, At, B0); PG8_MMA(1, 1, At, B1); PG8_BAR; PG8_SCHED;
.Lrw_P7_1d:
	s_waitcnt lgkmcnt(0)
	s_barrier
	s_setprio 1
	s_waitcnt lgkmcnt(0)
	v_mfma_f32_16x16x32_bf16 v[60:63], v[146:149], v[192:195], 0
	v_mfma_f32_16x16x32_bf16 v[56:59], v[168:171], v[192:195], 0
	v_mfma_f32_16x16x32_bf16 v[44:47], v[146:149], v[200:203], 0
	v_mfma_f32_16x16x32_bf16 v[40:43], v[168:171], v[200:203], 0
	v_mfma_f32_16x16x32_bf16 v[28:31], v[146:149], v[208:211], 0
	v_mfma_f32_16x16x32_bf16 v[24:27], v[168:171], v[208:211], 0
	v_mfma_f32_16x16x32_bf16 v[12:15], v[146:149], v[216:219], 0
	v_mfma_f32_16x16x32_bf16 v[8:11], v[168:171], v[216:219], 0
	v_mfma_f32_16x16x32_bf16 v[60:63], v[164:167], v[196:199], v[60:63]
	v_mfma_f32_16x16x32_bf16 v[56:59], v[172:175], v[196:199], v[56:59]
	v_mfma_f32_16x16x32_bf16 v[44:47], v[164:167], v[204:207], v[44:47]
	v_mfma_f32_16x16x32_bf16 v[40:43], v[172:175], v[204:207], v[40:43]
	v_mfma_f32_16x16x32_bf16 v[28:31], v[164:167], v[212:215], v[28:31]
	v_mfma_f32_16x16x32_bf16 v[24:27], v[172:175], v[212:215], v[24:27]
	v_mfma_f32_16x16x32_bf16 v[12:15], v[164:167], v[220:223], v[12:15]
	v_mfma_f32_16x16x32_bf16 v[8:11], v[172:175], v[220:223], v[8:11]
	s_setprio 0
	s_setprio 1
	v_mfma_f32_16x16x32_bf16 v[52:55], v[176:179], v[192:195], 0
	v_mfma_f32_16x16x32_bf16 v[48:51], v[184:187], v[192:195], 0
	v_mfma_f32_16x16x32_bf16 v[36:39], v[176:179], v[200:203], 0
	v_mfma_f32_16x16x32_bf16 v[32:35], v[184:187], v[200:203], 0
	v_mfma_f32_16x16x32_bf16 v[20:23], v[176:179], v[208:211], 0
	v_mfma_f32_16x16x32_bf16 v[16:19], v[184:187], v[208:211], 0
	v_mfma_f32_16x16x32_bf16 v[4:7], v[176:179], v[216:219], 0
	v_mfma_f32_16x16x32_bf16 v[0:3], v[184:187], v[216:219], 0
	v_mfma_f32_16x16x32_bf16 v[52:55], v[180:183], v[196:199], v[52:55]
	v_mfma_f32_16x16x32_bf16 v[48:51], v[188:191], v[196:199], v[48:51]
	v_mfma_f32_16x16x32_bf16 v[36:39], v[180:183], v[204:207], v[36:39]
	v_mfma_f32_16x16x32_bf16 v[32:35], v[188:191], v[204:207], v[32:35]
	v_mfma_f32_16x16x32_bf16 v[20:23], v[180:183], v[212:215], v[20:23]
	v_mfma_f32_16x16x32_bf16 v[16:19], v[188:191], v[212:215], v[16:19]
	v_mfma_f32_16x16x32_bf16 v[4:7], v[180:183], v[220:223], v[4:7]
	v_mfma_f32_16x16x32_bf16 v[0:3], v[188:191], v[220:223], v[0:3]
	s_setprio 0
	s_barrier
	s_branch .Lkmid_P7

; #define PG8_STAGE(bufoff, gbase, voff) do { _Pragma("unroll") for (int _i = 0; _i < 2; ++_i) \
;         __builtin_amdgcn_global_load_lds((const unsigned*)((const char*)(gbase) + (voff)[_i]), (PG8_LAS unsigned*)(lds + (bufoff) + ldsw + _i * 8192), 16, 0, PG8_LOAD_AUX); } while (0)
; #define PG8_LDA(dst, b, h) do { _Pragma("unroll") for (int m = 0; m < 4; ++m) _Pragma("unroll") for (int k = 0; k < 2; ++k) dst[m][k] = *(const PG8_LAS bf16x8*)(lds + PG8_SA(b, h) + aoff + m * 2048 + k * 1024); } while (0)
; #define PG8_LDB(dst, b, h) do { _Pragma("unroll") for (int n = 0; n < 2; ++n) _Pragma("unroll") for (int k = 0; k < 2; ++k) dst[n][k] = *(const PG8_LAS bf16x8*)(lds + PG8_SB(b, h) + boff + n * 2048 + k * 1024); } while (0)
; #define PG8_MMA(ai, bj, At, Bt) do { __builtin_amdgcn_s_setprio(1); _Pragma("unroll") for (int m = 0; m < 4; ++m) _Pragma("unroll") for (int n = 0; n < 2; ++n) _Pragma("unroll") for (int k = 0; k < 2; ++k) \
;         acc[ai][bj][m][n] = __builtin_amdgcn_mfma_f32_16x16x32_bf16(Bt[n][k], At[m][k], acc[ai][bj][m][n], 0, 0, 0); __builtin_amdgcn_s_setprio(0); } while (0)
; #define PG8_WAIT_V(n) asm volatile("s_waitcnt vmcnt(" #n ")" ::: "memory")
; #define PG8_WAIT_L(n) asm volatile("s_waitcnt lgkmcnt(" #n ")" ::: "memory")
; #define PG8_BAR __builtin_amdgcn_s_barrier()
; #define PG8_SCHED __builtin_amdgcn_sched_barrier(0)
; template <class Epi, class Sched, bool ALIGN_EPI = false, bool SP2 = false>
; __device__ __forceinline__ void gemm_phase(PG8_LAS unsigned char* lds, const Gemm g, const Sched& S, const Epi& E) {
;     ...
;             PG8_LDB(B0, 1, 0); PG8_LDB(B1, 1, 1); PG8_SCHED; PG8_LDA(At, 1, 0); PG8_STAGE(PG8_SA(0, 1), a2 + hstepA, voffA);
;             PG8_WAIT_V(8); PG8_WAIT_L(0); PG8_BAR; PG8_MMA(0, 0, At, B0); PG8_MMA(0, 1, At, B1); PG8_BAR; PG8_SCHED;
.Lkmid_P7:
	s_add_i32 s29, 0, 0x18000
	v_add_u32_e32 v163, s29, v156
	s_add_i32 s33, 0, 0x1c000
	ds_read_b128 v[146:149], v163
	ds_read_b128 v[164:167], v163 offset:1024
	ds_read_b128 v[168:171], v163 offset:2048
	ds_read_b128 v[172:175], v163 offset:3072
	v_add_u32_e32 v163, s33, v156
	ds_read_b128 v[176:179], v163
	ds_read_b128 v[180:183], v163 offset:1024
	ds_read_b128 v[184:187], v163 offset:2048
	ds_read_b128 v[188:191], v163 offset:3072
	s_add_u32 s30, s34, 0x40000
	s_addc_u32 s31, s35, 0
	s_mov_b32 m0, s47
	v_lshl_add_u64 v[230:231], s[30:31], 0, v[128:129]
	ds_read_b128 v[192:195], v160 offset:32768
	ds_read_b128 v[196:199], v160 offset:33792
	ds_read_b128 v[200:203], v160 offset:34816
	ds_read_b128 v[204:207], v160 offset:35840
	ds_read_b128 v[208:211], v160 offset:36864
	ds_read_b128 v[212:215], v160 offset:37888
	ds_read_b128 v[216:219], v160 offset:38912
	ds_read_b128 v[220:223], v160 offset:39936
	global_load_lds_dwordx4 v[230:231], off
	v_lshl_add_u64 v[230:231], s[30:31], 0, v[132:133]
	s_mov_b32 m0, s48
	s_nop 0
	global_load_lds_dwordx4 v[230:231], off
	s_waitcnt vmcnt(8)
	s_waitcnt lgkmcnt(0)
	s_barrier
	s_setprio 1
	s_waitcnt lgkmcnt(0)
	v_mfma_f32_16x16x32_bf16 v[124:127], v[146:149], v[192:195], v[124:127]
	v_mfma_f32_16x16x32_bf16 v[120:123], v[168:171], v[192:195], v[120:123]
	v_mfma_f32_16x16x32_bf16 v[108:111], v[146:149], v[200:203], v[108:111]
	v_mfma_f32_16x16x32_bf16 v[104:107], v[168:171], v[200:203], v[104:107]
	v_mfma_f32_16x16x32_bf16 v[92:95], v[146:149], v[208:211], v[92:95]
	v_mfma_f32_16x16x32_bf16 v[88:91], v[168:171], v[208:211], v[88:91]
	v_mfma_f32_16x16x32_bf16 v[76:79], v[146:149], v[216:219], v[76:79]
	v_mfma_f32_16x16x32_bf16 v[72:75], v[168:171], v[216:219], v[72:75]
	v_mfma_f32_16x16x32_bf16 v[124:127], v[164:167], v[196:199], v[124:127]
	v_mfma_f32_16x16x32_bf16 v[120:123], v[172:175], v[196:199], v[120:123]
	v_mfma_f32_16x16x32_bf16 v[108:111], v[164:167], v[204:207], v[108:111]
	v_mfma_f32_16x16x32_bf16 v[104:107], v[172:175], v[204:207], v[104:107]
	v_mfma_f32_16x16x32_bf16 v[92:95], v[164:167], v[212:215], v[92:95]
	v_mfma_f32_16x16x32_bf16 v[88:91], v[172:175], v[212:215], v[88:91]
	v_mfma_f32_16x16x32_bf16 v[76:79], v[164:167], v[220:223], v[76:79]
	v_mfma_f32_16x16x32_bf16 v[72:75], v[172:175], v[220:223], v[72:75]
	s_setprio 0
	s_setprio 1
	v_mfma_f32_16x16x32_bf16 v[116:119], v[176:179], v[192:195], v[116:119]
	v_mfma_f32_16x16x32_bf16 v[112:115], v[184:187], v[192:195], v[112:115]
	v_mfma_f32_16x16x32_bf16 v[100:103], v[176:179], v[200:203], v[100:103]
	v_mfma_f32_16x16x32_bf16 v[96:99], v[184:187], v[200:203], v[96:99]
	v_mfma_f32_16x16x32_bf16 v[84:87], v[176:179], v[208:211], v[84:87]
	v_mfma_f32_16x16x32_bf16 v[80:83], v[184:187], v[208:211], v[80:83]
	v_mfma_f32_16x16x32_bf16 v[68:71], v[176:179], v[216:219], v[68:71]
	v_mfma_f32_16x16x32_bf16 v[64:67], v[184:187], v[216:219], v[64:67]
	v_mfma_f32_16x16x32_bf16 v[116:119], v[180:183], v[196:199], v[116:119]
	v_mfma_f32_16x16x32_bf16 v[112:115], v[188:191], v[196:199], v[112:115]
	v_mfma_f32_16x16x32_bf16 v[100:103], v[180:183], v[204:207], v[100:103]
	v_mfma_f32_16x16x32_bf16 v[96:99], v[188:191], v[204:207], v[96:99]
	v_mfma_f32_16x16x32_bf16 v[84:87], v[180:183], v[212:215], v[84:87]
	v_mfma_f32_16x16x32_bf16 v[80:83], v[188:191], v[212:215], v[80:83]
	v_mfma_f32_16x16x32_bf16 v[68:71], v[180:183], v[220:223], v[68:71]
	v_mfma_f32_16x16x32_bf16 v[64:67], v[188:191], v[220:223], v[64:67]
	s_setprio 0
	s_barrier
; #define PG8_STAGE(bufoff, gbase, voff) do { _Pragma("unroll") for (int _i = 0; _i < 2; ++_i) \
;         __builtin_amdgcn_global_load_lds((const unsigned*)((const char*)(gbase) + (voff)[_i]), (PG8_LAS unsigned*)(lds + (bufoff) + ldsw + _i * 8192), 16, 0, PG8_LOAD_AUX); } while (0)
; #define PG8_LDA(dst, b, h) do { _Pragma("unroll") for (int m = 0; m < 4; ++m) _Pragma("unroll") for (int k = 0; k < 2; ++k) dst[m][k] = *(const PG8_LAS bf16x8*)(lds + PG8_SA(b, h) + aoff + m * 2048 + k * 1024); } while (0)
; #define PG8_MMA(ai, bj, At, Bt) do { __builtin_amdgcn_s_setprio(1); _Pragma("unroll") for (int m = 0; m < 4; ++m) _Pragma("unroll") for (int n = 0; n < 2; ++n) _Pragma("unroll") for (int k = 0; k < 2; ++k) \
;         acc[ai][bj][m][n] = __builtin_amdgcn_mfma_f32_16x16x32_bf16(Bt[n][k], At[m][k], acc[ai][bj][m][n], 0, 0, 0); __builtin_amdgcn_s_setprio(0); } while (0)
; #define PG8_WAIT_V(n) asm volatile("s_waitcnt vmcnt(" #n ")" ::: "memory")
; #define PG8_WAIT_L(n) asm volatile("s_waitcnt lgkmcnt(" #n ")" ::: "memory")
; #define PG8_BAR __builtin_amdgcn_s_barrier()
; #define PG8_SCHED __builtin_amdgcn_sched_barrier(0)
; __device__ __forceinline__ float rstd_from_slots(const float* slots, int row, int fq) {
;     const f32x4 s4 = *(const f32x4*)(slots + (size_t)row * 16 + 4 * fq);
; template <class Epi, class Sched, bool ALIGN_EPI = false, bool SP2 = false>
; __device__ __forceinline__ void gemm_phase(PG8_LAS unsigned char* lds, const Gemm g, const Sched& S, const Epi& E) {
;     ...
;             PG8_LDA(At, 1, 1); PG8_STAGE(PG8_SB(1, 0), b3, voffB); PG8_STAGE(PG8_SB(1, 1), b3 + hstepB, voffB); PG8_STAGE(PG8_SA(1, 0), a3, voffA);
;             PG8_WAIT_V(8); PG8_WAIT_L(0); PG8_BAR; PG8_MMA(1, 0, At, B0); PG8_MMA(1, 1, At, B1); PG8_BAR; PG8_SCHED;
;     ...
;         if constexpr (ALIGN_EPI) { if (wr == 0) PG8_BAR; }
	s_add_i32 s29, s29, s40
	v_lshl_add_u64 v[150:151], v[150:151], 0, s[8:9]
	s_mov_b32 m0, s29
	ds_read_b128 v[192:195], v160 offset:49152
	ds_read_b128 v[196:199], v160 offset:50176
	ds_read_b128 v[200:203], v160 offset:51200
	ds_read_b128 v[204:207], v160 offset:52224
	ds_read_b128 v[208:211], v160 offset:53248
	ds_read_b128 v[212:215], v160 offset:54272
	ds_read_b128 v[216:219], v160 offset:55296
	ds_read_b128 v[220:223], v160 offset:56320
	global_load_lds_dwordx4 v[150:151], off
	s_add_i32 m0, s29, 0x2000
	s_add_u32 s22, s22, 0x40080
	v_lshl_add_u64 v[150:151], v[224:225], 0, s[8:9]
	s_addc_u32 s23, s23, 0
	s_add_i32 s29, s33, s40
	global_load_lds_dwordx4 v[150:151], off
	v_lshl_add_u64 v[150:151], s[22:23], 0, v[130:131]
	s_mov_b32 m0, s29
	s_nop 0
	global_load_lds_dwordx4 v[150:151], off
	v_lshl_add_u64 v[150:151], s[22:23], 0, v[134:135]
	s_add_i32 m0, s29, 0x2000
	s_nop 0
	global_load_lds_dwordx4 v[150:151], off
	v_lshl_add_u64 v[150:151], v[226:227], 0, s[8:9]
	s_mov_b32 m0, s51
	s_nop 0
	global_load_lds_dwordx4 v[150:151], off
	v_lshl_add_u64 v[150:151], v[228:229], 0, s[8:9]
	s_mov_b32 m0, s52
	s_nop 0
	global_load_lds_dwordx4 v[150:151], off
	s_waitcnt vmcnt(8)
	s_waitcnt lgkmcnt(0)
	s_barrier
	s_setprio 1
	s_waitcnt lgkmcnt(0)
	v_mfma_f32_16x16x32_bf16 v[60:63], v[146:149], v[192:195], v[60:63]
	v_mfma_f32_16x16x32_bf16 v[56:59], v[168:171], v[192:195], v[56:59]
	v_mfma_f32_16x16x32_bf16 v[44:47], v[146:149], v[200:203], v[44:47]
	v_mfma_f32_16x16x32_bf16 v[40:43], v[168:171], v[200:203], v[40:43]
	v_mfma_f32_16x16x32_bf16 v[28:31], v[146:149], v[208:211], v[28:31]
	v_mfma_f32_16x16x32_bf16 v[24:27], v[168:171], v[208:211], v[24:27]
	v_mfma_f32_16x16x32_bf16 v[12:15], v[146:149], v[216:219], v[12:15]
	v_mfma_f32_16x16x32_bf16 v[8:11], v[168:171], v[216:219], v[8:11]
	v_mfma_f32_16x16x32_bf16 v[60:63], v[164:167], v[196:199], v[60:63]
	v_mfma_f32_16x16x32_bf16 v[56:59], v[172:175], v[196:199], v[56:59]
	v_mfma_f32_16x16x32_bf16 v[44:47], v[164:167], v[204:207], v[44:47]
	v_mfma_f32_16x16x32_bf16 v[40:43], v[172:175], v[204:207], v[40:43]
	v_mfma_f32_16x16x32_bf16 v[28:31], v[164:167], v[212:215], v[28:31]
	v_mfma_f32_16x16x32_bf16 v[24:27], v[172:175], v[212:215], v[24:27]
	v_mfma_f32_16x16x32_bf16 v[12:15], v[164:167], v[220:223], v[12:15]
	v_mfma_f32_16x16x32_bf16 v[8:11], v[172:175], v[220:223], v[8:11]
	s_setprio 0
	s_setprio 1
	v_mfma_f32_16x16x32_bf16 v[52:55], v[176:179], v[192:195], v[52:55]
	v_mfma_f32_16x16x32_bf16 v[48:51], v[184:187], v[192:195], v[48:51]
	v_mfma_f32_16x16x32_bf16 v[36:39], v[176:179], v[200:203], v[36:39]
	v_mfma_f32_16x16x32_bf16 v[32:35], v[184:187], v[200:203], v[32:35]
	v_mfma_f32_16x16x32_bf16 v[20:23], v[176:179], v[208:211], v[20:23]
	v_mfma_f32_16x16x32_bf16 v[16:19], v[184:187], v[208:211], v[16:19]
	v_mfma_f32_16x16x32_bf16 v[4:7], v[176:179], v[216:219], v[4:7]
	v_mfma_f32_16x16x32_bf16 v[0:3], v[184:187], v[216:219], v[0:3]
	v_mfma_f32_16x16x32_bf16 v[52:55], v[180:183], v[196:199], v[52:55]
	v_mfma_f32_16x16x32_bf16 v[48:51], v[188:191], v[196:199], v[48:51]
	v_mfma_f32_16x16x32_bf16 v[36:39], v[180:183], v[204:207], v[36:39]
	v_mfma_f32_16x16x32_bf16 v[32:35], v[188:191], v[204:207], v[32:35]
	v_mfma_f32_16x16x32_bf16 v[20:23], v[180:183], v[212:215], v[20:23]
	v_mfma_f32_16x16x32_bf16 v[16:19], v[188:191], v[212:215], v[16:19]
	v_mfma_f32_16x16x32_bf16 v[4:7], v[180:183], v[220:223], v[4:7]
	v_mfma_f32_16x16x32_bf16 v[0:3], v[188:191], v[220:223], v[0:3]
	s_setprio 0
	s_barrier
	s_add_i32 s28, s28, 2
	s_add_u32 s20, s20, 0x100
	s_addc_u32 s21, s21, 0
	s_add_u32 s26, s26, 0x100
	s_addc_u32 s27, s27, 0
	s_cmp_gt_u32 s28, 13
	s_cbranch_scc0 .LBB0_672
	s_mov_b32 s99, 1
	v_lshl_add_u32 v204, s0, 8, v152
	v_ashrrev_i32_e32 v205, 31, v204
	v_lshlrev_b64 v[204:205], 6, v[204:205]
	v_lshl_add_u64 v[204:205], v[136:137], 0, v[204:205]
	v_add_co_u32_e32 v206, vcc, 0x2000, v204
	s_nop 1
	v_addc_co_u32_e32 v207, vcc, 0, v205, vcc
	global_load_dwordx4 v[172:175], v[204:205], off
	global_load_dwordx4 v[176:179], v[204:205], off offset:1024
	global_load_dwordx4 v[180:183], v[204:205], off offset:2048
	global_load_dwordx4 v[184:187], v[204:205], off offset:3072
	global_load_dwordx4 v[188:191], v[206:207], off
	global_load_dwordx4 v[192:195], v[206:207], off offset:1024
	global_load_dwordx4 v[196:199], v[206:207], off offset:2048
	global_load_dwordx4 v[200:203], v[206:207], off offset:3072
	s_and_b64 vcc, exec, s[12:13]
	s_cbranch_vccz .LBB0_675
	s_barrier

; #define PG8_STAGE(bufoff, gbase, voff) do { _Pragma("unroll") for (int _i = 0; _i < 2; ++_i) \
;         __builtin_amdgcn_global_load_lds((const unsigned*)((const char*)(gbase) + (voff)[_i]), (PG8_LAS unsigned*)(lds + (bufoff) + ldsw + _i * 8192), 16, 0, PG8_LOAD_AUX); } while (0)
; #define PG8_WAIT_V(n) asm volatile("s_waitcnt vmcnt(" #n ")" ::: "memory")
; #define PG8_BAR __builtin_amdgcn_s_barrier()
; template <class Epi, class Sched, bool ALIGN_EPI = false, bool SP2 = false>
; __device__ __forceinline__ void gemm_phase(PG8_LAS unsigned char* lds, const Gemm g, const Sched& S, const Epi& E) {
;     ...
;     for (int i = 0; i < 2; ++i) { int R, C; stage_rc(tid * 16 + i * 8192, R, C); const int Rb = Epi::WIDE ? (64 * (R >> 5) + perm32(R & 31)) : (Epi::PERM ? ((R & ~31) + perm32(R & 31)) : R);
;         voffA[i] = (unsigned)(R * lda + C) * 2u; voffB[i] = (unsigned)(Rb * K + C) * 2u; }
;     const size_t kstep = (size_t)(BK * 2);
;     const size_t hstepA = (size_t)HALF * lda * 2, hstepB = (size_t)(Epi::WIDE ? 32 : HALF) * K * 2;
;     const size_t tstepA = 2 * hstepA, tstepB = (size_t)BM * K * 2;
;     const size_t apn = (size_t)g.a_pn_off * 2;
;     const unsigned ldsw = (unsigned)wid * 1024u;
;     const int aoff = lds_byte(wr * 64 + fr, fq * 8), boff = lds_byte(wc * 32 + fr, fq * 8);
;     ...
;         PG8_WAIT_V(2); PG8_BAR;
;         PG8_STAGE(PG8_SB(1, 0), cB + kstep, voffB); PG8_STAGE(PG8_SA(1, 0), cA + kstep, voffA); PG8_STAGE(PG8_SB(1, 1), cB + hstepB + kstep, voffB);
;         PG8_WAIT_V(6); PG8_BAR;
.LBB0_1105:
	s_lshl_b32 s1, s8, 5
	s_mov_b64 s[8:9], 0x80
	s_and_b32 s16, s1, 0x60
	s_add_i32 m0, s45, 0x18000
	v_lshl_add_u64 v[6:7], v[6:7], 0, s[8:9]
	s_lshl_b32 s13, s12, 13
	s_lshl_b32 s17, s16, 7
	s_waitcnt vmcnt(2)
	s_barrier
	global_load_lds_dwordx4 v[6:7], off
	v_lshl_add_u64 v[4:5], v[4:5], 0, s[8:9]
	s_add_i32 m0, s45, 0x1a000
	s_add_i32 s50, s45, 0x8000
	s_add_i32 s51, s45, 0xa000
	global_load_lds_dwordx4 v[4:5], off
	v_lshl_add_u64 v[0:1], v[0:1], 0, s[8:9]
	s_mov_b32 m0, s50
	s_add_u32 s14, s22, 0x40080
	global_load_lds_dwordx4 v[0:1], off
	v_lshl_add_u64 v[0:1], v[2:3], 0, s[8:9]
	s_mov_b32 m0, s51
	s_addc_u32 s15, s23, 0
	global_load_lds_dwordx4 v[0:1], off
	s_add_i32 m0, s45, 0x1c000
	v_lshl_add_u64 v[0:1], s[14:15], 0, v[132:133]
	global_load_lds_dwordx4 v[0:1], off
	v_lshl_add_u64 v[0:1], s[14:15], 0, v[128:129]
	s_add_i32 m0, s45, 0x1e000
	v_bfe_u32 v2, v154, 4, 2
	global_load_lds_dwordx4 v[0:1], off
	v_and_b32_e32 v1, 15, v154
	v_lshlrev_b32_e32 v0, 4, v2
	v_lshlrev_b32_e32 v3, 2, v154
	v_lshl_or_b32 v152, s12, 6, v1
	v_lshl_or_b32 v1, v1, 6, v0
	v_and_b32_e32 v3, 32, v3
	s_sext_i32_i8 s1, s2
	v_bitop3_b32 v4, v1, s13, v3 bitop3:0xde
	v_lshlrev_b32_e32 v1, 6, v154
	s_movk_i32 s2, 0x3c0
	v_and_or_b32 v1, v1, s2, v0
	v_bitop3_b32 v155, s17, v1, v3 bitop3:0xf6
	v_mov_b32_e32 v1, v133
	v_lshl_add_u64 v[136:137], s[82:83], 0, v[0:1]
	v_lshlrev_b32_e32 v0, 8, v154
	v_and_b32_e32 v0, 0x38000, v0
	v_lshlrev_b32_e32 v1, 11, v11
	v_or3_b32 v0, v9, v0, v1
	v_add_u32_e32 v138, v0, v10
	v_lshlrev_b32_e32 v0, 4, v8
	v_and_b32_e32 v0, 0x78000, v0
	s_waitcnt vmcnt(6)
	s_cmpk_lt_u32 s3, 0x100
	v_or3_b32 v0, v9, v0, v1
	s_cselect_b64 s[12:13], -1, 0
	v_add_u32_e32 v140, v0, v10
	s_add_i32 s54, 0, 0x10000
	s_add_i32 s55, 0, 0x14000
	v_mbcnt_lo_u32_b32 v0, -1, 0
	s_ashr_i32 s52, s86, 31
	s_mov_b32 s53, s86
	v_lshl_or_b32 v156, v2, 3, s16
	v_mov_b32_e32 v139, v133
	v_mov_b32_e32 v141, v133
	v_mov_b64_e32 v[142:143], 0xb00
	v_mov_b64_e32 v[144:145], 0xaff
	v_add_u32_e32 v157, s54, v155
	v_add_u32_e32 v158, s55, v155
	v_add_u32_e32 v159, 0, v4
	v_mbcnt_hi_u32_b32 v160, -1, v0
	v_mov_b32_e32 v161, 0x358637bd
	s_movk_i32 s56, 0x1600
	s_barrier
	s_mov_b32 s99, 0
	s_branch .LBB0_1108

; #define PG8_STAGE(bufoff, gbase, voff) do { _Pragma("unroll") for (int _i = 0; _i < 2; ++_i) \
;         __builtin_amdgcn_global_load_lds((const unsigned*)((const char*)(gbase) + (voff)[_i]), (PG8_LAS unsigned*)(lds + (bufoff) + ldsw + _i * 8192), 16, 0, PG8_LOAD_AUX); } while (0)
; #define PG8_LDA(dst, b, h) do { _Pragma("unroll") for (int m = 0; m < 4; ++m) _Pragma("unroll") for (int k = 0; k < 2; ++k) dst[m][k] = *(const PG8_LAS bf16x8*)(lds + PG8_SA(b, h) + aoff + m * 2048 + k * 1024); } while (0)
; #define PG8_LDB(dst, b, h) do { _Pragma("unroll") for (int n = 0; n < 2; ++n) _Pragma("unroll") for (int k = 0; k < 2; ++k) dst[n][k] = *(const PG8_LAS bf16x8*)(lds + PG8_SB(b, h) + boff + n * 2048 + k * 1024); } while (0)
; #define PG8_MMA(ai, bj, At, Bt) do { __builtin_amdgcn_s_setprio(1); _Pragma("unroll") for (int m = 0; m < 4; ++m) _Pragma("unroll") for (int n = 0; n < 2; ++n) _Pragma("unroll") for (int k = 0; k < 2; ++k) \
;         acc[ai][bj][m][n] = __builtin_amdgcn_mfma_f32_16x16x32_bf16(Bt[n][k], At[m][k], acc[ai][bj][m][n], 0, 0, 0); __builtin_amdgcn_s_setprio(0); } while (0)
; #define PG8_WAIT_V(n) asm volatile("s_waitcnt vmcnt(" #n ")" ::: "memory")
; #define PG8_WAIT_L(n) asm volatile("s_waitcnt lgkmcnt(" #n ")" ::: "memory")
; #define PG8_BAR __builtin_amdgcn_s_barrier()
; template <class Epi, class Sched, bool ALIGN_EPI = false, bool SP2 = false>
; __device__ __forceinline__ void gemm_phase(PG8_LAS unsigned char* lds, const Gemm g, const Sched& S, const Epi& E) {
;     ...
;         const char* nA = has_next ? (const char*)g.A + (size_t)nxt.pm * tstepA + (size_t)nxt.pn * apn : cA; const char* nB = has_next ? (const char*)g.Bt + (size_t)nxt.pn * tstepB : cB;
;         for (int t = 0; t < nt; t += 2) {
;             const bool last = (t == nt - 2);
;             const char* a1 = cA + (size_t)(t + 1) * kstep;
;             const char* a2 = last ? nA : cA + (size_t)(t + 2) * kstep; const char* b2 = last ? nB : cB + (size_t)(t + 2) * kstep;
;             const char* a3 = a2 + kstep; const char* b3 = b2 + kstep;
;             if (last && has_next) S.a_ready(nxt);
;             if constexpr (SP2) {
;             PG8_LDB(B0, 0, 0); PG8_LDB(B1, 0, 1); PG8_SCHED; PG8_LDA(At, 0, 0); PG8_STAGE(PG8_SA(1, 1), a1 + hstepA, voffA);
;             PG8_WAIT_V(8); PG8_WAIT_L(0); PG8_BAR; PG8_MMA(0, 0, At, B0); PG8_MMA(0, 1, At, B1); PG8_BAR; PG8_SCHED;
.LBB0_1110:
	s_ashr_i32 s17, s16, 31
	s_lshl_b64 s[18:19], s[16:17], 19
	s_add_u32 s18, s30, s18
	s_addc_u32 s19, s31, s19
	s_and_b64 s[24:25], s[2:3], exec
	s_cselect_b32 s17, s19, s21
	s_cselect_b32 s24, s18, s20
	s_ashr_i32 s15, s14, 31
	s_lshl_b64 s[26:27], s[14:15], 19
	s_add_u32 s36, s40, s26
	s_addc_u32 s37, s41, s27
	s_and_b64 s[26:27], s[2:3], exec
	s_cselect_b32 s15, s37, s23
	s_cselect_b32 s25, s36, s22
	s_add_u32 s20, s20, 0x40080
	s_addc_u32 s21, s21, 0
	s_add_u32 s26, s22, 0x100
	s_addc_u32 s27, s23, 0
	s_mov_b32 s28, -2
	ds_read_b128 v[146:149], v157
	ds_read_b128 v[162:165], v157 offset:1024
	ds_read_b128 v[166:169], v157 offset:2048
	ds_read_b128 v[170:173], v157 offset:3072
	ds_read_b128 v[174:177], v158
	ds_read_b128 v[178:181], v158 offset:1024
	ds_read_b128 v[182:185], v158 offset:2048
	ds_read_b128 v[186:189], v158 offset:3072
	s_add_u32 s22, s20, 0xfffc0080
	s_addc_u32 s23, s21, -1
	s_cmp_eq_u32 s28, 12
	s_cselect_b32 s35, s17, s23
	s_cselect_b32 s34, s24, s22
	s_cselect_b32 s23, s15, s27
	s_cselect_b32 s22, s25, s26
	v_lshl_add_u64 v[150:151], s[20:21], 0, v[138:139]
	s_add_i32 m0, s45, 0xc000
	ds_read_b128 v[190:193], v159
	ds_read_b128 v[194:197], v159 offset:1024
	ds_read_b128 v[198:201], v159 offset:2048
	ds_read_b128 v[202:205], v159 offset:3072
	ds_read_b128 v[206:209], v159 offset:4096
	ds_read_b128 v[210:213], v159 offset:5120
	ds_read_b128 v[214:217], v159 offset:6144
	ds_read_b128 v[218:221], v159 offset:7168
	global_load_lds_dwordx4 v[150:151], off
	v_lshl_add_u64 v[150:151], s[20:21], 0, v[140:141]
	s_add_i32 m0, s45, 0xe000
	s_nop 0
	global_load_lds_dwordx4 v[150:151], off
	s_cmp_lg_u32 s99, 0
	s_cbranch_scc1 .Lrw_P12_0r
	s_waitcnt vmcnt(8)
	s_branch .Lrw_P12_0d

; #define PG8_STAGE(bufoff, gbase, voff) do { _Pragma("unroll") for (int _i = 0; _i < 2; ++_i) \
;         __builtin_amdgcn_global_load_lds((const unsigned*)((const char*)(gbase) + (voff)[_i]), (PG8_LAS unsigned*)(lds + (bufoff) + ldsw + _i * 8192), 16, 0, PG8_LOAD_AUX); } while (0)
; #define PG8_LDA(dst, b, h) do { _Pragma("unroll") for (int m = 0; m < 4; ++m) _Pragma("unroll") for (int k = 0; k < 2; ++k) dst[m][k] = *(const PG8_LAS bf16x8*)(lds + PG8_SA(b, h) + aoff + m * 2048 + k * 1024); } while (0)
; #define PG8_MMA(ai, bj, At, Bt) do { __builtin_amdgcn_s_setprio(1); _Pragma("unroll") for (int m = 0; m < 4; ++m) _Pragma("unroll") for (int n = 0; n < 2; ++n) _Pragma("unroll") for (int k = 0; k < 2; ++k) \
;         acc[ai][bj][m][n] = __builtin_amdgcn_mfma_f32_16x16x32_bf16(Bt[n][k], At[m][k], acc[ai][bj][m][n], 0, 0, 0); __builtin_amdgcn_s_setprio(0); } while (0)
; #define PG8_WAIT_V(n) asm volatile("s_waitcnt vmcnt(" #n ")" ::: "memory")
; #define PG8_WAIT_L(n) asm volatile("s_waitcnt lgkmcnt(" #n ")" ::: "memory")
; #define PG8_BAR __builtin_amdgcn_s_barrier()
; #define PG8_SCHED __builtin_amdgcn_sched_barrier(0)
; template <class Epi, class Sched, bool ALIGN_EPI = false, bool SP2 = false>
; __device__ __forceinline__ void gemm_phase(PG8_LAS unsigned char* lds, const Gemm g, const Sched& S, const Epi& E) {
;     ...
;             PG8_WAIT_V(8); PG8_WAIT_L(0); PG8_BAR; PG8_MMA(0, 0, At, B0); PG8_MMA(0, 1, At, B1); PG8_BAR; PG8_SCHED;
;             PG8_LDA(At, 0, 1); PG8_STAGE(PG8_SB(0, 0), b2, voffB); PG8_STAGE(PG8_SB(0, 1), b2 + hstepB, voffB); PG8_STAGE(PG8_SA(0, 0), a2, voffA);
;             PG8_WAIT_V(8); PG8_WAIT_L(0); PG8_BAR; PG8_MMA(1, 0, At, B0); PG8_MMA(1, 1, At, B1); PG8_BAR; PG8_SCHED;
.Lrw_P12_0d:
	s_waitcnt lgkmcnt(0)
	s_barrier
	s_setprio 1
	s_waitcnt lgkmcnt(0)
	v_mfma_f32_16x16x32_bf16 v[124:127], v[146:149], v[190:193], 0
	v_mfma_f32_16x16x32_bf16 v[120:123], v[166:169], v[190:193], 0
	v_mfma_f32_16x16x32_bf16 v[108:111], v[146:149], v[198:201], 0
	v_mfma_f32_16x16x32_bf16 v[104:107], v[166:169], v[198:201], 0
	v_mfma_f32_16x16x32_bf16 v[92:95], v[146:149], v[206:209], 0
	v_mfma_f32_16x16x32_bf16 v[88:91], v[166:169], v[206:209], 0
	v_mfma_f32_16x16x32_bf16 v[76:79], v[146:149], v[214:217], 0
	v_mfma_f32_16x16x32_bf16 v[72:75], v[166:169], v[214:217], 0
	v_mfma_f32_16x16x32_bf16 v[124:127], v[162:165], v[194:197], v[124:127]
	v_mfma_f32_16x16x32_bf16 v[120:123], v[170:173], v[194:197], v[120:123]
	v_mfma_f32_16x16x32_bf16 v[108:111], v[162:165], v[202:205], v[108:111]
	v_mfma_f32_16x16x32_bf16 v[104:107], v[170:173], v[202:205], v[104:107]
	v_mfma_f32_16x16x32_bf16 v[92:95], v[162:165], v[210:213], v[92:95]
	v_mfma_f32_16x16x32_bf16 v[88:91], v[170:173], v[210:213], v[88:91]
	v_mfma_f32_16x16x32_bf16 v[76:79], v[162:165], v[218:221], v[76:79]
	v_mfma_f32_16x16x32_bf16 v[72:75], v[170:173], v[218:221], v[72:75]
	s_setprio 0
	s_setprio 1
	v_mfma_f32_16x16x32_bf16 v[116:119], v[174:177], v[190:193], 0
	v_mfma_f32_16x16x32_bf16 v[112:115], v[182:185], v[190:193], 0
	v_mfma_f32_16x16x32_bf16 v[100:103], v[174:177], v[198:201], 0
	v_mfma_f32_16x16x32_bf16 v[96:99], v[182:185], v[198:201], 0
	v_mfma_f32_16x16x32_bf16 v[84:87], v[174:177], v[206:209], 0
	v_mfma_f32_16x16x32_bf16 v[80:83], v[182:185], v[206:209], 0
	v_mfma_f32_16x16x32_bf16 v[68:71], v[174:177], v[214:217], 0
	v_mfma_f32_16x16x32_bf16 v[64:67], v[182:185], v[214:217], 0
	v_mfma_f32_16x16x32_bf16 v[116:119], v[178:181], v[194:197], v[116:119]
	v_mfma_f32_16x16x32_bf16 v[112:115], v[186:189], v[194:197], v[112:115]
	v_mfma_f32_16x16x32_bf16 v[100:103], v[178:181], v[202:205], v[100:103]
	v_mfma_f32_16x16x32_bf16 v[96:99], v[186:189], v[202:205], v[96:99]
	v_mfma_f32_16x16x32_bf16 v[84:87], v[178:181], v[210:213], v[84:87]
	v_mfma_f32_16x16x32_bf16 v[80:83], v[186:189], v[210:213], v[80:83]
	v_mfma_f32_16x16x32_bf16 v[68:71], v[178:181], v[218:221], v[68:71]
	v_mfma_f32_16x16x32_bf16 v[64:67], v[186:189], v[218:221], v[64:67]
	s_setprio 0
	s_barrier
	s_add_i32 s29, s54, s42
	v_lshl_add_u64 v[150:151], s[22:23], 0, v[132:133]
	s_mov_b32 m0, s29
	ds_read_b128 v[190:193], v159 offset:16384
	ds_read_b128 v[194:197], v159 offset:17408
	ds_read_b128 v[198:201], v159 offset:18432
	ds_read_b128 v[202:205], v159 offset:19456
	ds_read_b128 v[206:209], v159 offset:20480
	ds_read_b128 v[210:213], v159 offset:21504
	ds_read_b128 v[214:217], v159 offset:22528
	ds_read_b128 v[218:221], v159 offset:23552
	global_load_lds_dwordx4 v[150:151], off
	s_add_i32 m0, s29, 0x2000
	s_add_u32 s30, s22, 0x40000
	v_lshl_add_u64 v[222:223], s[22:23], 0, v[128:129]
	s_addc_u32 s31, s23, 0
	s_add_i32 s29, s55, s42
	global_load_lds_dwordx4 v[222:223], off
	v_lshl_add_u64 v[224:225], s[30:31], 0, v[132:133]
	s_mov_b32 m0, s29
	v_lshl_add_u64 v[226:227], s[34:35], 0, v[130:131]
	global_load_lds_dwordx4 v[224:225], off
	v_lshl_add_u64 v[224:225], s[30:31], 0, v[128:129]
	s_add_i32 m0, s29, 0x2000
	s_nop 0
	global_load_lds_dwordx4 v[224:225], off
	v_lshl_add_u64 v[224:225], s[34:35], 0, v[134:135]
	s_mov_b32 m0, s45
	s_nop 0
	global_load_lds_dwordx4 v[224:225], off
	s_mov_b32 m0, s46
	s_nop 0
	global_load_lds_dwordx4 v[226:227], off
	s_cmp_lg_u32 s99, 0
	s_cbranch_scc1 .Lrw_P12_1r
	s_waitcnt vmcnt(8)
	s_branch .Lrw_P12_1d

; #define PG8_MMA(ai, bj, At, Bt) do { __builtin_amdgcn_s_setprio(1); _Pragma("unroll") for (int m = 0; m < 4; ++m) _Pragma("unroll") for (int n = 0; n < 2; ++n) _Pragma("unroll") for (int k = 0; k < 2; ++k) \
;         acc[ai][bj][m][n] = __builtin_amdgcn_mfma_f32_16x16x32_bf16(Bt[n][k], At[m][k], acc[ai][bj][m][n], 0, 0, 0); __builtin_amdgcn_s_setprio(0); } while (0)
; #define PG8_WAIT_V(n) asm volatile("s_waitcnt vmcnt(" #n ")" ::: "memory")
; #define PG8_WAIT_L(n) asm volatile("s_waitcnt lgkmcnt(" #n ")" ::: "memory")
; #define PG8_BAR __builtin_amdgcn_s_barrier()
; #define PG8_SCHED __builtin_amdgcn_sched_barrier(0)
; template <class Epi, class Sched, bool ALIGN_EPI = false, bool SP2 = false>
; __device__ __forceinline__ void gemm_phase(PG8_LAS unsigned char* lds, const Gemm g, const Sched& S, const Epi& E) {
;     ...
;             PG8_WAIT_V(8); PG8_WAIT_L(0); PG8_BAR; PG8_MMA(1, 0, At, B0); PG8_MMA(1, 1, At, B1); PG8_BAR; PG8_SCHED;
.Lrw_P12_1d:
	s_waitcnt lgkmcnt(0)
	s_barrier
	s_setprio 1
	s_waitcnt lgkmcnt(0)
	v_mfma_f32_16x16x32_bf16 v[60:63], v[146:149], v[190:193], 0
	v_mfma_f32_16x16x32_bf16 v[56:59], v[166:169], v[190:193], 0
	v_mfma_f32_16x16x32_bf16 v[44:47], v[146:149], v[198:201], 0
	v_mfma_f32_16x16x32_bf16 v[40:43], v[166:169], v[198:201], 0
	v_mfma_f32_16x16x32_bf16 v[28:31], v[146:149], v[206:209], 0
	v_mfma_f32_16x16x32_bf16 v[24:27], v[166:169], v[206:209], 0
	v_mfma_f32_16x16x32_bf16 v[12:15], v[146:149], v[214:217], 0
	v_mfma_f32_16x16x32_bf16 v[8:11], v[166:169], v[214:217], 0
	v_mfma_f32_16x16x32_bf16 v[60:63], v[162:165], v[194:197], v[60:63]
	v_mfma_f32_16x16x32_bf16 v[56:59], v[170:173], v[194:197], v[56:59]
	v_mfma_f32_16x16x32_bf16 v[44:47], v[162:165], v[202:205], v[44:47]
	v_mfma_f32_16x16x32_bf16 v[40:43], v[170:173], v[202:205], v[40:43]
	v_mfma_f32_16x16x32_bf16 v[28:31], v[162:165], v[210:213], v[28:31]
	v_mfma_f32_16x16x32_bf16 v[24:27], v[170:173], v[210:213], v[24:27]
	v_mfma_f32_16x16x32_bf16 v[12:15], v[162:165], v[218:221], v[12:15]
	v_mfma_f32_16x16x32_bf16 v[8:11], v[170:173], v[218:221], v[8:11]
	s_setprio 0
	s_setprio 1
	v_mfma_f32_16x16x32_bf16 v[52:55], v[174:177], v[190:193], 0
	v_mfma_f32_16x16x32_bf16 v[48:51], v[182:185], v[190:193], 0
	v_mfma_f32_16x16x32_bf16 v[36:39], v[174:177], v[198:201], 0
	v_mfma_f32_16x16x32_bf16 v[32:35], v[182:185], v[198:201], 0
	v_mfma_f32_16x16x32_bf16 v[20:23], v[174:177], v[206:209], 0
	v_mfma_f32_16x16x32_bf16 v[16:19], v[182:185], v[206:209], 0
	v_mfma_f32_16x16x32_bf16 v[4:7], v[174:177], v[214:217], 0
	v_mfma_f32_16x16x32_bf16 v[0:3], v[182:185], v[214:217], 0
	v_mfma_f32_16x16x32_bf16 v[52:55], v[178:181], v[194:197], v[52:55]
	v_mfma_f32_16x16x32_bf16 v[48:51], v[186:189], v[194:197], v[48:51]
	v_mfma_f32_16x16x32_bf16 v[36:39], v[178:181], v[202:205], v[36:39]
	v_mfma_f32_16x16x32_bf16 v[32:35], v[186:189], v[202:205], v[32:35]
	v_mfma_f32_16x16x32_bf16 v[20:23], v[178:181], v[210:213], v[20:23]
	v_mfma_f32_16x16x32_bf16 v[16:19], v[186:189], v[210:213], v[16:19]
	v_mfma_f32_16x16x32_bf16 v[4:7], v[178:181], v[218:221], v[4:7]
	v_mfma_f32_16x16x32_bf16 v[0:3], v[186:189], v[218:221], v[0:3]
	s_setprio 0
	s_barrier
	s_branch .Lkmid_P12

; #define PG8_STAGE(bufoff, gbase, voff) do { _Pragma("unroll") for (int _i = 0; _i < 2; ++_i) \
;         __builtin_amdgcn_global_load_lds((const unsigned*)((const char*)(gbase) + (voff)[_i]), (PG8_LAS unsigned*)(lds + (bufoff) + ldsw + _i * 8192), 16, 0, PG8_LOAD_AUX); } while (0)
; #define PG8_LDA(dst, b, h) do { _Pragma("unroll") for (int m = 0; m < 4; ++m) _Pragma("unroll") for (int k = 0; k < 2; ++k) dst[m][k] = *(const PG8_LAS bf16x8*)(lds + PG8_SA(b, h) + aoff + m * 2048 + k * 1024); } while (0)
; #define PG8_LDB(dst, b, h) do { _Pragma("unroll") for (int n = 0; n < 2; ++n) _Pragma("unroll") for (int k = 0; k < 2; ++k) dst[n][k] = *(const PG8_LAS bf16x8*)(lds + PG8_SB(b, h) + boff + n * 2048 + k * 1024); } while (0)
; #define PG8_MMA(ai, bj, At, Bt) do { __builtin_amdgcn_s_setprio(1); _Pragma("unroll") for (int m = 0; m < 4; ++m) _Pragma("unroll") for (int n = 0; n < 2; ++n) _Pragma("unroll") for (int k = 0; k < 2; ++k) \
;         acc[ai][bj][m][n] = __builtin_amdgcn_mfma_f32_16x16x32_bf16(Bt[n][k], At[m][k], acc[ai][bj][m][n], 0, 0, 0); __builtin_amdgcn_s_setprio(0); } while (0)
; #define PG8_WAIT_V(n) asm volatile("s_waitcnt vmcnt(" #n ")" ::: "memory")
; #define PG8_WAIT_L(n) asm volatile("s_waitcnt lgkmcnt(" #n ")" ::: "memory")
; #define PG8_BAR __builtin_amdgcn_s_barrier()
; #define PG8_SCHED __builtin_amdgcn_sched_barrier(0)
; template <class Epi, class Sched, bool ALIGN_EPI = false, bool SP2 = false>
; __device__ __forceinline__ void gemm_phase(PG8_LAS unsigned char* lds, const Gemm g, const Sched& S, const Epi& E) {
;     ...
;             PG8_LDB(B0, 1, 0); PG8_LDB(B1, 1, 1); PG8_SCHED; PG8_LDA(At, 1, 0); PG8_STAGE(PG8_SA(0, 1), a2 + hstepA, voffA);
;             PG8_WAIT_V(8); PG8_WAIT_L(0); PG8_BAR; PG8_MMA(0, 0, At, B0); PG8_MMA(0, 1, At, B1); PG8_BAR; PG8_SCHED;
.Lkmid_P12:
	s_add_i32 s29, 0, 0x18000
	s_add_i32 s33, 0, 0x1c000
	v_add_u32_e32 v170, s29, v155
	v_add_u32_e32 v186, s33, v155
	ds_read_b128 v[146:149], v170
	ds_read_b128 v[162:165], v170 offset:1024
	ds_read_b128 v[166:169], v170 offset:2048
	ds_read_b128 v[170:173], v170 offset:3072
	ds_read_b128 v[174:177], v186
	ds_read_b128 v[178:181], v186 offset:1024
	ds_read_b128 v[182:185], v186 offset:2048
	ds_read_b128 v[186:189], v186 offset:3072
	s_add_u32 s30, s34, 0x40000
	s_addc_u32 s31, s35, 0
	s_mov_b32 m0, s47
	v_lshl_add_u64 v[228:229], s[30:31], 0, v[134:135]
	ds_read_b128 v[190:193], v159 offset:32768
	ds_read_b128 v[194:197], v159 offset:33792
	ds_read_b128 v[198:201], v159 offset:34816
	ds_read_b128 v[202:205], v159 offset:35840
	ds_read_b128 v[206:209], v159 offset:36864
	ds_read_b128 v[210:213], v159 offset:37888
	ds_read_b128 v[214:217], v159 offset:38912
	ds_read_b128 v[218:221], v159 offset:39936
	global_load_lds_dwordx4 v[228:229], off
	v_lshl_add_u64 v[228:229], s[30:31], 0, v[130:131]
	s_mov_b32 m0, s48
	s_nop 0
	global_load_lds_dwordx4 v[228:229], off
	s_waitcnt vmcnt(8)
	s_waitcnt lgkmcnt(0)
	s_barrier
	s_setprio 1
	s_waitcnt lgkmcnt(0)
	v_mfma_f32_16x16x32_bf16 v[124:127], v[146:149], v[190:193], v[124:127]
	v_mfma_f32_16x16x32_bf16 v[120:123], v[166:169], v[190:193], v[120:123]
	v_mfma_f32_16x16x32_bf16 v[108:111], v[146:149], v[198:201], v[108:111]
	v_mfma_f32_16x16x32_bf16 v[104:107], v[166:169], v[198:201], v[104:107]
	v_mfma_f32_16x16x32_bf16 v[92:95], v[146:149], v[206:209], v[92:95]
	v_mfma_f32_16x16x32_bf16 v[88:91], v[166:169], v[206:209], v[88:91]
	v_mfma_f32_16x16x32_bf16 v[76:79], v[146:149], v[214:217], v[76:79]
	v_mfma_f32_16x16x32_bf16 v[72:75], v[166:169], v[214:217], v[72:75]
	v_mfma_f32_16x16x32_bf16 v[124:127], v[162:165], v[194:197], v[124:127]
	v_mfma_f32_16x16x32_bf16 v[120:123], v[170:173], v[194:197], v[120:123]
	v_mfma_f32_16x16x32_bf16 v[108:111], v[162:165], v[202:205], v[108:111]
	v_mfma_f32_16x16x32_bf16 v[104:107], v[170:173], v[202:205], v[104:107]
	v_mfma_f32_16x16x32_bf16 v[92:95], v[162:165], v[210:213], v[92:95]
	v_mfma_f32_16x16x32_bf16 v[88:91], v[170:173], v[210:213], v[88:91]
	v_mfma_f32_16x16x32_bf16 v[76:79], v[162:165], v[218:221], v[76:79]
	v_mfma_f32_16x16x32_bf16 v[72:75], v[170:173], v[218:221], v[72:75]
	s_setprio 0
	s_setprio 1
	v_mfma_f32_16x16x32_bf16 v[116:119], v[174:177], v[190:193], v[116:119]
	v_mfma_f32_16x16x32_bf16 v[112:115], v[182:185], v[190:193], v[112:115]
	v_mfma_f32_16x16x32_bf16 v[100:103], v[174:177], v[198:201], v[100:103]
	v_mfma_f32_16x16x32_bf16 v[96:99], v[182:185], v[198:201], v[96:99]
	v_mfma_f32_16x16x32_bf16 v[84:87], v[174:177], v[206:209], v[84:87]
	v_mfma_f32_16x16x32_bf16 v[80:83], v[182:185], v[206:209], v[80:83]
	v_mfma_f32_16x16x32_bf16 v[68:71], v[174:177], v[214:217], v[68:71]
	v_mfma_f32_16x16x32_bf16 v[64:67], v[182:185], v[214:217], v[64:67]
	v_mfma_f32_16x16x32_bf16 v[116:119], v[178:181], v[194:197], v[116:119]
	v_mfma_f32_16x16x32_bf16 v[112:115], v[186:189], v[194:197], v[112:115]
	v_mfma_f32_16x16x32_bf16 v[100:103], v[178:181], v[202:205], v[100:103]
	v_mfma_f32_16x16x32_bf16 v[96:99], v[186:189], v[202:205], v[96:99]
	v_mfma_f32_16x16x32_bf16 v[84:87], v[178:181], v[210:213], v[84:87]
	v_mfma_f32_16x16x32_bf16 v[80:83], v[186:189], v[210:213], v[80:83]
	v_mfma_f32_16x16x32_bf16 v[68:71], v[178:181], v[218:221], v[68:71]
	v_mfma_f32_16x16x32_bf16 v[64:67], v[186:189], v[218:221], v[64:67]
	s_setprio 0
	s_barrier
; #define PG8_STAGE(bufoff, gbase, voff) do { _Pragma("unroll") for (int _i = 0; _i < 2; ++_i) \
;         __builtin_amdgcn_global_load_lds((const unsigned*)((const char*)(gbase) + (voff)[_i]), (PG8_LAS unsigned*)(lds + (bufoff) + ldsw + _i * 8192), 16, 0, PG8_LOAD_AUX); } while (0)
; #define PG8_LDA(dst, b, h) do { _Pragma("unroll") for (int m = 0; m < 4; ++m) _Pragma("unroll") for (int k = 0; k < 2; ++k) dst[m][k] = *(const PG8_LAS bf16x8*)(lds + PG8_SA(b, h) + aoff + m * 2048 + k * 1024); } while (0)
; #define PG8_MMA(ai, bj, At, Bt) do { __builtin_amdgcn_s_setprio(1); _Pragma("unroll") for (int m = 0; m < 4; ++m) _Pragma("unroll") for (int n = 0; n < 2; ++n) _Pragma("unroll") for (int k = 0; k < 2; ++k) \
;         acc[ai][bj][m][n] = __builtin_amdgcn_mfma_f32_16x16x32_bf16(Bt[n][k], At[m][k], acc[ai][bj][m][n], 0, 0, 0); __builtin_amdgcn_s_setprio(0); } while (0)
; #define PG8_WAIT_V(n) asm volatile("s_waitcnt vmcnt(" #n ")" ::: "memory")
; #define PG8_WAIT_L(n) asm volatile("s_waitcnt lgkmcnt(" #n ")" ::: "memory")
; #define PG8_BAR __builtin_amdgcn_s_barrier()
; #define PG8_SCHED __builtin_amdgcn_sched_barrier(0)
; __device__ __forceinline__ float rstd_from_slots(const float* slots, int row, int fq) {
;     const f32x4 s4 = *(const f32x4*)(slots + (size_t)row * 16 + 4 * fq);
; template <class Epi, class Sched, bool ALIGN_EPI = false, bool SP2 = false>
; __device__ __forceinline__ void gemm_phase(PG8_LAS unsigned char* lds, const Gemm g, const Sched& S, const Epi& E) {
;     ...
;             PG8_LDA(At, 1, 1); PG8_STAGE(PG8_SB(1, 0), b3, voffB); PG8_STAGE(PG8_SB(1, 1), b3 + hstepB, voffB); PG8_STAGE(PG8_SA(1, 0), a3, voffA);
;             PG8_WAIT_V(8); PG8_WAIT_L(0); PG8_BAR; PG8_MMA(1, 0, At, B0); PG8_MMA(1, 1, At, B1); PG8_BAR; PG8_SCHED;
;     ...
;         if constexpr (ALIGN_EPI) { if (wr == 0) PG8_BAR; }
	s_add_i32 s29, s29, s42
	v_lshl_add_u64 v[150:151], v[150:151], 0, s[8:9]
	s_mov_b32 m0, s29
	ds_read_b128 v[190:193], v159 offset:49152
	ds_read_b128 v[194:197], v159 offset:50176
	ds_read_b128 v[198:201], v159 offset:51200
	ds_read_b128 v[202:205], v159 offset:52224
	ds_read_b128 v[206:209], v159 offset:53248
	ds_read_b128 v[210:213], v159 offset:54272
	ds_read_b128 v[214:217], v159 offset:55296
	ds_read_b128 v[218:221], v159 offset:56320
	global_load_lds_dwordx4 v[150:151], off
	s_add_i32 m0, s29, 0x2000
	s_add_u32 s22, s22, 0x40080
	v_lshl_add_u64 v[150:151], v[222:223], 0, s[8:9]
	s_addc_u32 s23, s23, 0
	s_add_i32 s29, s33, s42
	global_load_lds_dwordx4 v[150:151], off
	v_lshl_add_u64 v[150:151], s[22:23], 0, v[132:133]
	s_mov_b32 m0, s29
	s_nop 0
	global_load_lds_dwordx4 v[150:151], off
	v_lshl_add_u64 v[150:151], s[22:23], 0, v[128:129]
	s_add_i32 m0, s29, 0x2000
	s_nop 0
	global_load_lds_dwordx4 v[150:151], off
	v_lshl_add_u64 v[150:151], v[224:225], 0, s[8:9]
	s_mov_b32 m0, s50
	s_nop 0
	global_load_lds_dwordx4 v[150:151], off
	v_lshl_add_u64 v[150:151], v[226:227], 0, s[8:9]
	s_mov_b32 m0, s51
	s_nop 0
	global_load_lds_dwordx4 v[150:151], off
	s_waitcnt vmcnt(8)
	s_waitcnt lgkmcnt(0)
	s_barrier
	s_setprio 1
	s_waitcnt lgkmcnt(0)
	v_mfma_f32_16x16x32_bf16 v[60:63], v[146:149], v[190:193], v[60:63]
	v_mfma_f32_16x16x32_bf16 v[56:59], v[166:169], v[190:193], v[56:59]
	v_mfma_f32_16x16x32_bf16 v[44:47], v[146:149], v[198:201], v[44:47]
	v_mfma_f32_16x16x32_bf16 v[40:43], v[166:169], v[198:201], v[40:43]
	v_mfma_f32_16x16x32_bf16 v[28:31], v[146:149], v[206:209], v[28:31]
	v_mfma_f32_16x16x32_bf16 v[24:27], v[166:169], v[206:209], v[24:27]
	v_mfma_f32_16x16x32_bf16 v[12:15], v[146:149], v[214:217], v[12:15]
	v_mfma_f32_16x16x32_bf16 v[8:11], v[166:169], v[214:217], v[8:11]
	v_mfma_f32_16x16x32_bf16 v[60:63], v[162:165], v[194:197], v[60:63]
	v_mfma_f32_16x16x32_bf16 v[56:59], v[170:173], v[194:197], v[56:59]
	v_mfma_f32_16x16x32_bf16 v[44:47], v[162:165], v[202:205], v[44:47]
	v_mfma_f32_16x16x32_bf16 v[40:43], v[170:173], v[202:205], v[40:43]
	v_mfma_f32_16x16x32_bf16 v[28:31], v[162:165], v[210:213], v[28:31]
	v_mfma_f32_16x16x32_bf16 v[24:27], v[170:173], v[210:213], v[24:27]
	v_mfma_f32_16x16x32_bf16 v[12:15], v[162:165], v[218:221], v[12:15]
	v_mfma_f32_16x16x32_bf16 v[8:11], v[170:173], v[218:221], v[8:11]
	s_setprio 0
	s_setprio 1
	v_mfma_f32_16x16x32_bf16 v[52:55], v[174:177], v[190:193], v[52:55]
	v_mfma_f32_16x16x32_bf16 v[48:51], v[182:185], v[190:193], v[48:51]
	v_mfma_f32_16x16x32_bf16 v[36:39], v[174:177], v[198:201], v[36:39]
	v_mfma_f32_16x16x32_bf16 v[32:35], v[182:185], v[198:201], v[32:35]
	v_mfma_f32_16x16x32_bf16 v[20:23], v[174:177], v[206:209], v[20:23]
	v_mfma_f32_16x16x32_bf16 v[16:19], v[182:185], v[206:209], v[16:19]
	v_mfma_f32_16x16x32_bf16 v[4:7], v[174:177], v[214:217], v[4:7]
	v_mfma_f32_16x16x32_bf16 v[0:3], v[182:185], v[214:217], v[0:3]
	v_mfma_f32_16x16x32_bf16 v[52:55], v[178:181], v[194:197], v[52:55]
	v_mfma_f32_16x16x32_bf16 v[48:51], v[186:189], v[194:197], v[48:51]
	v_mfma_f32_16x16x32_bf16 v[36:39], v[178:181], v[202:205], v[36:39]
	v_mfma_f32_16x16x32_bf16 v[32:35], v[186:189], v[202:205], v[32:35]
	v_mfma_f32_16x16x32_bf16 v[20:23], v[178:181], v[210:213], v[20:23]
	v_mfma_f32_16x16x32_bf16 v[16:19], v[186:189], v[210:213], v[16:19]
	v_mfma_f32_16x16x32_bf16 v[4:7], v[178:181], v[218:221], v[4:7]
	v_mfma_f32_16x16x32_bf16 v[0:3], v[186:189], v[218:221], v[0:3]
	s_setprio 0
	s_barrier
	s_add_i32 s28, s28, 2
	s_add_u32 s20, s20, 0x100
	s_addc_u32 s21, s21, 0
	s_add_u32 s26, s26, 0x100
	s_addc_u32 s27, s27, 0
	s_cmp_gt_u32 s28, 13
	s_cbranch_scc0 .LBB0_1111
	s_mov_b32 s99, 1
	v_lshl_add_u32 v204, s0, 8, v152
	v_ashrrev_i32_e32 v205, 31, v204
	v_lshlrev_b64 v[204:205], 6, v[204:205]
	v_lshl_add_u64 v[204:205], v[136:137], 0, v[204:205]
	v_add_co_u32_e32 v206, vcc, 0x2000, v204
	s_nop 1
	v_addc_co_u32_e32 v207, vcc, 0, v205, vcc
	global_load_dwordx4 v[172:175], v[204:205], off
	global_load_dwordx4 v[176:179], v[204:205], off offset:1024
	global_load_dwordx4 v[180:183], v[204:205], off offset:2048
	global_load_dwordx4 v[184:187], v[204:205], off offset:3072
	global_load_dwordx4 v[188:191], v[206:207], off
	global_load_dwordx4 v[192:195], v[206:207], off offset:1024
	global_load_dwordx4 v[196:199], v[206:207], off offset:2048
	global_load_dwordx4 v[200:203], v[206:207], off offset:3072
	s_and_b64 vcc, exec, s[12:13]
	s_cbranch_vccz .LBB0_1114
	s_barrier

; __global__ void __launch_bounds__(NTHREADS, 2) trunk_fwd(Args args) {
	.amdhsa_kernel _Z9trunk_fwd4Args
		.amdhsa_group_segment_fixed_size 0
		.amdhsa_private_segment_fixed_size 0
		.amdhsa_kernarg_size 376
		.amdhsa_user_sgpr_count 2
		.amdhsa_user_sgpr_dispatch_ptr 0
		.amdhsa_user_sgpr_queue_ptr 0
		.amdhsa_user_sgpr_kernarg_segment_ptr 1
		.amdhsa_user_sgpr_dispatch_id 0
		.amdhsa_user_sgpr_kernarg_preload_length 0
		.amdhsa_user_sgpr_kernarg_preload_offset 0
		.amdhsa_user_sgpr_private_segment_size 0
		.amdhsa_uses_dynamic_stack 0
		.amdhsa_enable_private_segment 0
		.amdhsa_system_sgpr_workgroup_id_x 1
		.amdhsa_system_sgpr_workgroup_id_y 0
		.amdhsa_system_sgpr_workgroup_id_z 0
		.amdhsa_system_sgpr_workgroup_info 0
		.amdhsa_system_vgpr_workitem_id 2
		.amdhsa_next_free_vgpr 240
		.amdhsa_next_free_sgpr 100
		.amdhsa_accum_offset 240
		.amdhsa_reserve_vcc 1
		.amdhsa_float_round_mode_32 0
		.amdhsa_float_round_mode_16_64 0
		.amdhsa_float_denorm_mode_32 3
		.amdhsa_float_denorm_mode_16_64 3
		.amdhsa_dx10_clamp 1
		.amdhsa_ieee_mode 1
		.amdhsa_fp16_overflow 0
		.amdhsa_tg_split 0
		.amdhsa_exception_fp_ieee_invalid_op 0
		.amdhsa_exception_fp_denorm_src 0
		.amdhsa_exception_fp_ieee_div_zero 0
		.amdhsa_exception_fp_ieee_overflow 0
		.amdhsa_exception_fp_ieee_underflow 0
		.amdhsa_exception_fp_ieee_inexact 0
		.amdhsa_exception_int_div_zero 0
	.end_amdhsa_kernel

; __global__ void __launch_bounds__(NTHREADS, 2) trunk_fwd(Args args) {
amdhsa.kernels:
  - .agpr_count:     0
    .args:
      - .offset:         0
        .size:           120
        .value_kind:     by_value
      - .offset:         120
        .size:           4
        .value_kind:     hidden_block_count_x
      - .offset:         124
        .size:           4
        .value_kind:     hidden_block_count_y
      - .offset:         128
        .size:           4
        .value_kind:     hidden_block_count_z
      - .offset:         132
        .size:           2
        .value_kind:     hidden_group_size_x
      - .offset:         134
        .size:           2
        .value_kind:     hidden_group_size_y
      - .offset:         136
        .size:           2
        .value_kind:     hidden_group_size_z
      - .offset:         138
        .size:           2
        .value_kind:     hidden_remainder_x
      - .offset:         140
        .size:           2
        .value_kind:     hidden_remainder_y
      - .offset:         142
        .size:           2
        .value_kind:     hidden_remainder_z
      - .offset:         160
        .size:           8
        .value_kind:     hidden_global_offset_x
      - .offset:         168
        .size:           8
        .value_kind:     hidden_global_offset_y
      - .offset:         176
        .size:           8
        .value_kind:     hidden_global_offset_z
      - .offset:         184
        .size:           2
        .value_kind:     hidden_grid_dims
      - .offset:         208
        .size:           8
        .value_kind:     hidden_multigrid_sync_arg
      - .offset:         240
        .size:           4
        .value_kind:     hidden_dynamic_lds_size
    .group_segment_fixed_size: 0
    .kernarg_segment_align: 8
    .kernarg_segment_size: 376
    .language:       OpenCL C
    .language_version:
      - 2
      - 0
    .max_flat_workgroup_size: 512
    .name:           _Z9trunk_fwd4Args
    .private_segment_fixed_size: 0
    .sgpr_count:     106
    .sgpr_spill_count: 107
    .symbol:         _Z9trunk_fwd4Args.kd
    .uniform_work_group_size: 1
    .uses_dynamic_stack: false
    .vgpr_count:     240
    .vgpr_spill_count: 0
    .wavefront_size: 64
